# K-loops: removed the redundant mid-block s_setprio 0 / s_setprio 1 pair between the two 16-MFMA groups of each super-phase
# baseline (speedup 1.0000x reference)
.LBB0_189:
	ds_read_b128 v[156:159], v152
	ds_read_b128 v[160:163], v152 offset:1024
	ds_read_b128 v[164:167], v152 offset:2048
	ds_read_b128 v[168:171], v152 offset:3072
	ds_read_b128 v[172:175], v153
	ds_read_b128 v[176:179], v153 offset:1024
	ds_read_b128 v[180:183], v153 offset:2048
	ds_read_b128 v[184:187], v153 offset:3072
	s_add_u32 s82, s80, 0xfffc0080
	s_addc_u32 s83, s81, -1
	s_cmp_eq_u32 s96, 12
	s_cselect_b32 s85, s10, s83
	s_cselect_b32 s84, s11, s82
	s_cselect_b32 s83, s63, s95
	s_cselect_b32 s82, s65, s94
	v_lshl_add_u64 v[144:145], s[80:81], 0, v[136:137]
	s_add_i32 m0, s45, 0xc000
	ds_read_b128 v[188:191], v154
	ds_read_b128 v[192:195], v154 offset:1024
	ds_read_b128 v[200:203], v154 offset:2048
	ds_read_b128 v[204:207], v154 offset:3072
	ds_read_b128 v[208:211], v154 offset:4096
	ds_read_b128 v[212:215], v154 offset:5120
	ds_read_b128 v[216:219], v154 offset:6144
	ds_read_b128 v[224:227], v154 offset:7168
	global_load_lds_dwordx4 v[144:145], off
	v_lshl_add_u64 v[144:145], s[80:81], 0, v[138:139]
	s_add_i32 m0, s45, 0xe000
	s_nop 0
	global_load_lds_dwordx4 v[144:145], off
	s_waitcnt vmcnt(8)
	s_waitcnt lgkmcnt(0)
	s_barrier
	s_setprio 1
	s_waitcnt lgkmcnt(0)
	v_mfma_f32_16x16x32_bf16 v[124:127], v[156:159], v[188:191], v[124:127]
	v_mfma_f32_16x16x32_bf16 v[120:123], v[164:167], v[188:191], v[120:123]
	v_mfma_f32_16x16x32_bf16 v[108:111], v[156:159], v[200:203], v[108:111]
	v_mfma_f32_16x16x32_bf16 v[104:107], v[164:167], v[200:203], v[104:107]
	v_mfma_f32_16x16x32_bf16 v[92:95], v[156:159], v[208:211], v[92:95]
	v_mfma_f32_16x16x32_bf16 v[88:91], v[164:167], v[208:211], v[88:91]
	v_mfma_f32_16x16x32_bf16 v[76:79], v[156:159], v[216:219], v[76:79]
	v_mfma_f32_16x16x32_bf16 v[72:75], v[164:167], v[216:219], v[72:75]
	v_mfma_f32_16x16x32_bf16 v[124:127], v[160:163], v[192:195], v[124:127]
	v_mfma_f32_16x16x32_bf16 v[120:123], v[168:171], v[192:195], v[120:123]
	v_mfma_f32_16x16x32_bf16 v[108:111], v[160:163], v[204:207], v[108:111]
	v_mfma_f32_16x16x32_bf16 v[104:107], v[168:171], v[204:207], v[104:107]
	v_mfma_f32_16x16x32_bf16 v[92:95], v[160:163], v[212:215], v[92:95]
	v_mfma_f32_16x16x32_bf16 v[88:91], v[168:171], v[212:215], v[88:91]
	v_mfma_f32_16x16x32_bf16 v[76:79], v[160:163], v[224:227], v[76:79]
	v_mfma_f32_16x16x32_bf16 v[72:75], v[168:171], v[224:227], v[72:75]
	v_mfma_f32_16x16x32_bf16 v[116:119], v[172:175], v[188:191], v[116:119]
	v_mfma_f32_16x16x32_bf16 v[112:115], v[180:183], v[188:191], v[112:115]
	v_mfma_f32_16x16x32_bf16 v[100:103], v[172:175], v[200:203], v[100:103]
	v_mfma_f32_16x16x32_bf16 v[96:99], v[180:183], v[200:203], v[96:99]
	v_mfma_f32_16x16x32_bf16 v[84:87], v[172:175], v[208:211], v[84:87]
	v_mfma_f32_16x16x32_bf16 v[80:83], v[180:183], v[208:211], v[80:83]
	v_mfma_f32_16x16x32_bf16 v[68:71], v[172:175], v[216:219], v[68:71]
	v_mfma_f32_16x16x32_bf16 v[64:67], v[180:183], v[216:219], v[64:67]
	v_mfma_f32_16x16x32_bf16 v[116:119], v[176:179], v[192:195], v[116:119]
	v_mfma_f32_16x16x32_bf16 v[112:115], v[184:187], v[192:195], v[112:115]
	v_mfma_f32_16x16x32_bf16 v[100:103], v[176:179], v[204:207], v[100:103]
	v_mfma_f32_16x16x32_bf16 v[96:99], v[184:187], v[204:207], v[96:99]
	v_mfma_f32_16x16x32_bf16 v[84:87], v[176:179], v[212:215], v[84:87]
	v_mfma_f32_16x16x32_bf16 v[80:83], v[184:187], v[212:215], v[80:83]
	v_mfma_f32_16x16x32_bf16 v[68:71], v[176:179], v[224:227], v[68:71]
	v_mfma_f32_16x16x32_bf16 v[64:67], v[184:187], v[224:227], v[64:67]
	s_setprio 0
	s_barrier
	s_add_i32 s97, s90, s2
	v_lshl_add_u64 v[144:145], s[82:83], 0, v[132:133]
	s_mov_b32 m0, s97
	ds_read_b128 v[188:191], v154 offset:16384
	ds_read_b128 v[192:195], v154 offset:17408
	ds_read_b128 v[200:203], v154 offset:18432
	ds_read_b128 v[204:207], v154 offset:19456
	ds_read_b128 v[208:211], v154 offset:20480
	ds_read_b128 v[212:215], v154 offset:21504
	ds_read_b128 v[216:219], v154 offset:22528
	ds_read_b128 v[224:227], v154 offset:23552
	global_load_lds_dwordx4 v[144:145], off
	s_add_i32 m0, s97, 0x2000
	s_add_u32 vcc_lo, s82, 0x40000
	v_lshl_add_u64 v[196:197], s[82:83], 0, v[128:129]
	s_addc_u32 vcc_hi, s83, 0
	s_add_i32 s97, s91, s2
	global_load_lds_dwordx4 v[196:197], off
	v_lshl_add_u64 v[220:221], vcc, 0, v[132:133]
	s_mov_b32 m0, s97
	v_lshl_add_u64 v[228:229], s[84:85], 0, v[130:131]
	global_load_lds_dwordx4 v[220:221], off
	v_lshl_add_u64 v[220:221], vcc, 0, v[128:129]
	s_add_i32 m0, s97, 0x2000
	s_nop 0
	global_load_lds_dwordx4 v[220:221], off
	v_lshl_add_u64 v[220:221], s[84:85], 0, v[134:135]
	s_mov_b32 m0, s45
	s_nop 0
	global_load_lds_dwordx4 v[220:221], off
	s_mov_b32 m0, s70
	s_nop 0
	global_load_lds_dwordx4 v[228:229], off
	s_waitcnt vmcnt(8)
	s_waitcnt lgkmcnt(0)
	s_barrier
	s_setprio 1
	s_waitcnt lgkmcnt(0)
	v_mfma_f32_16x16x32_bf16 v[60:63], v[156:159], v[188:191], v[60:63]
	v_mfma_f32_16x16x32_bf16 v[56:59], v[164:167], v[188:191], v[56:59]
	v_mfma_f32_16x16x32_bf16 v[44:47], v[156:159], v[200:203], v[44:47]
	v_mfma_f32_16x16x32_bf16 v[40:43], v[164:167], v[200:203], v[40:43]
	v_mfma_f32_16x16x32_bf16 v[28:31], v[156:159], v[208:211], v[28:31]
	v_mfma_f32_16x16x32_bf16 v[24:27], v[164:167], v[208:211], v[24:27]
	v_mfma_f32_16x16x32_bf16 v[12:15], v[156:159], v[216:219], v[12:15]
	v_mfma_f32_16x16x32_bf16 v[8:11], v[164:167], v[216:219], v[8:11]
	v_mfma_f32_16x16x32_bf16 v[60:63], v[160:163], v[192:195], v[60:63]
	v_mfma_f32_16x16x32_bf16 v[56:59], v[168:171], v[192:195], v[56:59]
	v_mfma_f32_16x16x32_bf16 v[44:47], v[160:163], v[204:207], v[44:47]
	v_mfma_f32_16x16x32_bf16 v[40:43], v[168:171], v[204:207], v[40:43]
	v_mfma_f32_16x16x32_bf16 v[28:31], v[160:163], v[212:215], v[28:31]
	v_mfma_f32_16x16x32_bf16 v[24:27], v[168:171], v[212:215], v[24:27]
	v_mfma_f32_16x16x32_bf16 v[12:15], v[160:163], v[224:227], v[12:15]
	v_mfma_f32_16x16x32_bf16 v[8:11], v[168:171], v[224:227], v[8:11]
	v_mfma_f32_16x16x32_bf16 v[52:55], v[172:175], v[188:191], v[52:55]
	v_mfma_f32_16x16x32_bf16 v[48:51], v[180:183], v[188:191], v[48:51]
	v_mfma_f32_16x16x32_bf16 v[36:39], v[172:175], v[200:203], v[36:39]
	v_mfma_f32_16x16x32_bf16 v[32:35], v[180:183], v[200:203], v[32:35]
	v_mfma_f32_16x16x32_bf16 v[20:23], v[172:175], v[208:211], v[20:23]
	v_mfma_f32_16x16x32_bf16 v[16:19], v[180:183], v[208:211], v[16:19]
	v_mfma_f32_16x16x32_bf16 v[4:7], v[172:175], v[216:219], v[4:7]
	v_mfma_f32_16x16x32_bf16 v[0:3], v[180:183], v[216:219], v[0:3]
	v_mfma_f32_16x16x32_bf16 v[52:55], v[176:179], v[192:195], v[52:55]
	v_mfma_f32_16x16x32_bf16 v[48:51], v[184:187], v[192:195], v[48:51]
	v_mfma_f32_16x16x32_bf16 v[36:39], v[176:179], v[204:207], v[36:39]
	v_mfma_f32_16x16x32_bf16 v[32:35], v[184:187], v[204:207], v[32:35]
	v_mfma_f32_16x16x32_bf16 v[20:23], v[176:179], v[212:215], v[20:23]
	v_mfma_f32_16x16x32_bf16 v[16:19], v[184:187], v[212:215], v[16:19]
	v_mfma_f32_16x16x32_bf16 v[4:7], v[176:179], v[224:227], v[4:7]
	v_mfma_f32_16x16x32_bf16 v[0:3], v[184:187], v[224:227], v[0:3]
	s_setprio 0
	s_barrier
	s_add_i32 s97, 0, 0x18000
	v_add_u32_e32 v155, s97, v147
	s_add_i32 vcc_lo, 0, 0x1c000
	ds_read_b128 v[156:159], v155
	ds_read_b128 v[160:163], v155 offset:1024
	ds_read_b128 v[164:167], v155 offset:2048
	ds_read_b128 v[168:171], v155 offset:3072
	v_add_u32_e32 v155, vcc_lo, v147
	ds_read_b128 v[172:175], v155
	ds_read_b128 v[176:179], v155 offset:1024
	ds_read_b128 v[180:183], v155 offset:2048
	ds_read_b128 v[184:187], v155 offset:3072
	s_add_u32 s84, s84, 0x40000
	s_addc_u32 s85, s85, 0
	s_mov_b32 m0, s71
	v_lshl_add_u64 v[230:231], s[84:85], 0, v[134:135]
	ds_read_b128 v[188:191], v154 offset:32768
	ds_read_b128 v[192:195], v154 offset:33792
	ds_read_b128 v[200:203], v154 offset:34816
	ds_read_b128 v[204:207], v154 offset:35840
	ds_read_b128 v[208:211], v154 offset:36864
	ds_read_b128 v[212:215], v154 offset:37888
	ds_read_b128 v[216:219], v154 offset:38912
	ds_read_b128 v[224:227], v154 offset:39936
	global_load_lds_dwordx4 v[230:231], off
	v_lshl_add_u64 v[230:231], s[84:85], 0, v[130:131]
	s_mov_b32 m0, s75
	s_nop 0
	global_load_lds_dwordx4 v[230:231], off
	s_waitcnt vmcnt(8)
	s_waitcnt lgkmcnt(0)
	s_barrier
	s_setprio 1
	s_waitcnt lgkmcnt(0)
	v_mfma_f32_16x16x32_bf16 v[124:127], v[156:159], v[188:191], v[124:127]
	v_mfma_f32_16x16x32_bf16 v[120:123], v[164:167], v[188:191], v[120:123]
	v_mfma_f32_16x16x32_bf16 v[108:111], v[156:159], v[200:203], v[108:111]
	v_mfma_f32_16x16x32_bf16 v[104:107], v[164:167], v[200:203], v[104:107]
	v_mfma_f32_16x16x32_bf16 v[92:95], v[156:159], v[208:211], v[92:95]
	v_mfma_f32_16x16x32_bf16 v[88:91], v[164:167], v[208:211], v[88:91]
	v_mfma_f32_16x16x32_bf16 v[76:79], v[156:159], v[216:219], v[76:79]
	v_mfma_f32_16x16x32_bf16 v[72:75], v[164:167], v[216:219], v[72:75]
	v_mfma_f32_16x16x32_bf16 v[124:127], v[160:163], v[192:195], v[124:127]
	v_mfma_f32_16x16x32_bf16 v[120:123], v[168:171], v[192:195], v[120:123]
	v_mfma_f32_16x16x32_bf16 v[108:111], v[160:163], v[204:207], v[108:111]
	v_mfma_f32_16x16x32_bf16 v[104:107], v[168:171], v[204:207], v[104:107]
	v_mfma_f32_16x16x32_bf16 v[92:95], v[160:163], v[212:215], v[92:95]
	v_mfma_f32_16x16x32_bf16 v[88:91], v[168:171], v[212:215], v[88:91]
	v_mfma_f32_16x16x32_bf16 v[76:79], v[160:163], v[224:227], v[76:79]
	v_mfma_f32_16x16x32_bf16 v[72:75], v[168:171], v[224:227], v[72:75]
	v_mfma_f32_16x16x32_bf16 v[116:119], v[172:175], v[188:191], v[116:119]
	v_mfma_f32_16x16x32_bf16 v[112:115], v[180:183], v[188:191], v[112:115]
	v_mfma_f32_16x16x32_bf16 v[100:103], v[172:175], v[200:203], v[100:103]
	v_mfma_f32_16x16x32_bf16 v[96:99], v[180:183], v[200:203], v[96:99]
	v_mfma_f32_16x16x32_bf16 v[84:87], v[172:175], v[208:211], v[84:87]
	v_mfma_f32_16x16x32_bf16 v[80:83], v[180:183], v[208:211], v[80:83]
	v_mfma_f32_16x16x32_bf16 v[68:71], v[172:175], v[216:219], v[68:71]
	v_mfma_f32_16x16x32_bf16 v[64:67], v[180:183], v[216:219], v[64:67]
	v_mfma_f32_16x16x32_bf16 v[116:119], v[176:179], v[192:195], v[116:119]
	v_mfma_f32_16x16x32_bf16 v[112:115], v[184:187], v[192:195], v[112:115]
	v_mfma_f32_16x16x32_bf16 v[100:103], v[176:179], v[204:207], v[100:103]
	v_mfma_f32_16x16x32_bf16 v[96:99], v[184:187], v[204:207], v[96:99]
	v_mfma_f32_16x16x32_bf16 v[84:87], v[176:179], v[212:215], v[84:87]
	v_mfma_f32_16x16x32_bf16 v[80:83], v[184:187], v[212:215], v[80:83]
	v_mfma_f32_16x16x32_bf16 v[68:71], v[176:179], v[224:227], v[68:71]
	v_mfma_f32_16x16x32_bf16 v[64:67], v[184:187], v[224:227], v[64:67]
	s_setprio 0
	s_barrier
	s_add_i32 s84, s97, s2
	v_lshl_add_u64 v[144:145], v[144:145], 0, s[8:9]
	s_mov_b32 m0, s84
	ds_read_b128 v[188:191], v154 offset:49152
	ds_read_b128 v[192:195], v154 offset:50176
	ds_read_b128 v[200:203], v154 offset:51200
	ds_read_b128 v[204:207], v154 offset:52224
	ds_read_b128 v[208:211], v154 offset:53248
	ds_read_b128 v[212:215], v154 offset:54272
	ds_read_b128 v[216:219], v154 offset:55296
	ds_read_b128 v[224:227], v154 offset:56320
	global_load_lds_dwordx4 v[144:145], off
	s_add_i32 m0, s84, 0x2000
	s_add_u32 s82, s82, 0x40080
	v_lshl_add_u64 v[144:145], v[196:197], 0, s[8:9]
	s_addc_u32 s83, s83, 0
	s_add_i32 s84, vcc_lo, s2
	global_load_lds_dwordx4 v[144:145], off
	v_lshl_add_u64 v[144:145], s[82:83], 0, v[132:133]
	s_mov_b32 m0, s84
	s_nop 0
	global_load_lds_dwordx4 v[144:145], off
	v_lshl_add_u64 v[144:145], s[82:83], 0, v[128:129]
	s_add_i32 m0, s84, 0x2000
	s_nop 0
	global_load_lds_dwordx4 v[144:145], off
	v_lshl_add_u64 v[144:145], v[220:221], 0, s[8:9]
	s_mov_b32 m0, s86
	s_nop 0
	global_load_lds_dwordx4 v[144:145], off
	v_lshl_add_u64 v[144:145], v[228:229], 0, s[8:9]
	s_mov_b32 m0, s87
	s_nop 0
	global_load_lds_dwordx4 v[144:145], off
	s_waitcnt vmcnt(8)
	s_waitcnt lgkmcnt(0)
	s_barrier
	s_setprio 1
	s_waitcnt lgkmcnt(0)
	v_mfma_f32_16x16x32_bf16 v[60:63], v[156:159], v[188:191], v[60:63]
	v_mfma_f32_16x16x32_bf16 v[56:59], v[164:167], v[188:191], v[56:59]
	v_mfma_f32_16x16x32_bf16 v[44:47], v[156:159], v[200:203], v[44:47]
	v_mfma_f32_16x16x32_bf16 v[40:43], v[164:167], v[200:203], v[40:43]
	v_mfma_f32_16x16x32_bf16 v[28:31], v[156:159], v[208:211], v[28:31]
	v_mfma_f32_16x16x32_bf16 v[24:27], v[164:167], v[208:211], v[24:27]
	v_mfma_f32_16x16x32_bf16 v[12:15], v[156:159], v[216:219], v[12:15]
	v_mfma_f32_16x16x32_bf16 v[8:11], v[164:167], v[216:219], v[8:11]
	v_mfma_f32_16x16x32_bf16 v[60:63], v[160:163], v[192:195], v[60:63]
	v_mfma_f32_16x16x32_bf16 v[56:59], v[168:171], v[192:195], v[56:59]
	v_mfma_f32_16x16x32_bf16 v[44:47], v[160:163], v[204:207], v[44:47]
	v_mfma_f32_16x16x32_bf16 v[40:43], v[168:171], v[204:207], v[40:43]
	v_mfma_f32_16x16x32_bf16 v[28:31], v[160:163], v[212:215], v[28:31]
	v_mfma_f32_16x16x32_bf16 v[24:27], v[168:171], v[212:215], v[24:27]
	v_mfma_f32_16x16x32_bf16 v[12:15], v[160:163], v[224:227], v[12:15]
	v_mfma_f32_16x16x32_bf16 v[8:11], v[168:171], v[224:227], v[8:11]
	v_mfma_f32_16x16x32_bf16 v[52:55], v[172:175], v[188:191], v[52:55]
	v_mfma_f32_16x16x32_bf16 v[48:51], v[180:183], v[188:191], v[48:51]
	v_mfma_f32_16x16x32_bf16 v[36:39], v[172:175], v[200:203], v[36:39]
	v_mfma_f32_16x16x32_bf16 v[32:35], v[180:183], v[200:203], v[32:35]
	v_mfma_f32_16x16x32_bf16 v[20:23], v[172:175], v[208:211], v[20:23]
	v_mfma_f32_16x16x32_bf16 v[16:19], v[180:183], v[208:211], v[16:19]
	v_mfma_f32_16x16x32_bf16 v[4:7], v[172:175], v[216:219], v[4:7]
	v_mfma_f32_16x16x32_bf16 v[0:3], v[180:183], v[216:219], v[0:3]
	v_mfma_f32_16x16x32_bf16 v[52:55], v[176:179], v[192:195], v[52:55]
	v_mfma_f32_16x16x32_bf16 v[48:51], v[184:187], v[192:195], v[48:51]
	v_mfma_f32_16x16x32_bf16 v[36:39], v[176:179], v[204:207], v[36:39]
	v_mfma_f32_16x16x32_bf16 v[32:35], v[184:187], v[204:207], v[32:35]
	v_mfma_f32_16x16x32_bf16 v[20:23], v[176:179], v[212:215], v[20:23]
	v_mfma_f32_16x16x32_bf16 v[16:19], v[184:187], v[212:215], v[16:19]
	v_mfma_f32_16x16x32_bf16 v[4:7], v[176:179], v[224:227], v[4:7]
	v_mfma_f32_16x16x32_bf16 v[0:3], v[184:187], v[224:227], v[0:3]
	s_setprio 0
	s_barrier
	s_add_i32 s96, s96, 2
	s_add_u32 s80, s80, 0x100
	s_addc_u32 s81, s81, 0
	s_add_u32 s94, s94, 0x100
	s_addc_u32 s95, s95, 0
	s_cmp_gt_u32 s96, 13
	s_cbranch_scc0 .LBB0_189
	s_and_b64 vcc, exec, s[60:61]
	s_cbranch_vccz .LBB0_192
	s_barrier

.LBB0_340:
	ds_read_b128 v[144:147], v171
	ds_read_b128 v[148:151], v171 offset:1024
	ds_read_b128 v[152:155], v171 offset:2048
	ds_read_b128 v[156:159], v171 offset:3072
	ds_read_b128 v[160:163], v172
	ds_read_b128 v[164:167], v172 offset:1024
	ds_read_b128 v[176:179], v172 offset:2048
	ds_read_b128 v[180:183], v172 offset:3072
	s_add_u32 s56, s54, 0xfff50080
	s_addc_u32 s57, s55, -1
	s_cmp_eq_u32 s84, 40
	s_cselect_b32 s59, s7, s57
	s_cselect_b32 s58, s6, s56
	s_cselect_b32 s57, s51, s83
	s_cselect_b32 s56, s50, s82
	v_lshl_add_u64 v[196:197], s[54:55], 0, v[136:137]
	s_add_i32 m0, s17, 0xc000
	ds_read_b128 v[184:187], v173
	ds_read_b128 v[188:191], v173 offset:1024
	ds_read_b128 v[192:195], v173 offset:2048
	ds_read_b128 v[200:203], v173 offset:3072
	ds_read_b128 v[204:207], v173 offset:4096
	ds_read_b128 v[208:211], v173 offset:5120
	ds_read_b128 v[212:215], v173 offset:6144
	ds_read_b128 v[216:219], v173 offset:7168
	global_load_lds_dwordx4 v[196:197], off
	v_lshl_add_u64 v[196:197], s[54:55], 0, v[138:139]
	s_add_i32 m0, s17, 0xe000
	s_nop 0
	global_load_lds_dwordx4 v[196:197], off
	s_waitcnt vmcnt(8)
	s_waitcnt lgkmcnt(0)
	s_barrier
	s_setprio 1
	s_waitcnt lgkmcnt(0)
	v_mfma_f32_16x16x32_bf16 v[124:127], v[144:147], v[184:187], v[124:127]
	v_mfma_f32_16x16x32_bf16 v[120:123], v[152:155], v[184:187], v[120:123]
	v_mfma_f32_16x16x32_bf16 v[108:111], v[144:147], v[192:195], v[108:111]
	v_mfma_f32_16x16x32_bf16 v[104:107], v[152:155], v[192:195], v[104:107]
	v_mfma_f32_16x16x32_bf16 v[92:95], v[144:147], v[204:207], v[92:95]
	v_mfma_f32_16x16x32_bf16 v[88:91], v[152:155], v[204:207], v[88:91]
	v_mfma_f32_16x16x32_bf16 v[76:79], v[144:147], v[212:215], v[76:79]
	v_mfma_f32_16x16x32_bf16 v[72:75], v[152:155], v[212:215], v[72:75]
	v_mfma_f32_16x16x32_bf16 v[124:127], v[148:151], v[188:191], v[124:127]
	v_mfma_f32_16x16x32_bf16 v[120:123], v[156:159], v[188:191], v[120:123]
	v_mfma_f32_16x16x32_bf16 v[108:111], v[148:151], v[200:203], v[108:111]
	v_mfma_f32_16x16x32_bf16 v[104:107], v[156:159], v[200:203], v[104:107]
	v_mfma_f32_16x16x32_bf16 v[92:95], v[148:151], v[208:211], v[92:95]
	v_mfma_f32_16x16x32_bf16 v[88:91], v[156:159], v[208:211], v[88:91]
	v_mfma_f32_16x16x32_bf16 v[76:79], v[148:151], v[216:219], v[76:79]
	v_mfma_f32_16x16x32_bf16 v[72:75], v[156:159], v[216:219], v[72:75]
	v_mfma_f32_16x16x32_bf16 v[116:119], v[160:163], v[184:187], v[116:119]
	v_mfma_f32_16x16x32_bf16 v[112:115], v[176:179], v[184:187], v[112:115]
	v_mfma_f32_16x16x32_bf16 v[100:103], v[160:163], v[192:195], v[100:103]
	v_mfma_f32_16x16x32_bf16 v[96:99], v[176:179], v[192:195], v[96:99]
	v_mfma_f32_16x16x32_bf16 v[84:87], v[160:163], v[204:207], v[84:87]
	v_mfma_f32_16x16x32_bf16 v[80:83], v[176:179], v[204:207], v[80:83]
	v_mfma_f32_16x16x32_bf16 v[68:71], v[160:163], v[212:215], v[68:71]
	v_mfma_f32_16x16x32_bf16 v[64:67], v[176:179], v[212:215], v[64:67]
	v_mfma_f32_16x16x32_bf16 v[116:119], v[164:167], v[188:191], v[116:119]
	v_mfma_f32_16x16x32_bf16 v[112:115], v[180:183], v[188:191], v[112:115]
	v_mfma_f32_16x16x32_bf16 v[100:103], v[164:167], v[200:203], v[100:103]
	v_mfma_f32_16x16x32_bf16 v[96:99], v[180:183], v[200:203], v[96:99]
	v_mfma_f32_16x16x32_bf16 v[84:87], v[164:167], v[208:211], v[84:87]
	v_mfma_f32_16x16x32_bf16 v[80:83], v[180:183], v[208:211], v[80:83]
	v_mfma_f32_16x16x32_bf16 v[68:71], v[164:167], v[216:219], v[68:71]
	v_mfma_f32_16x16x32_bf16 v[64:67], v[180:183], v[216:219], v[64:67]
	s_setprio 0
	s_barrier
	s_add_i32 s85, s78, s16
	v_lshl_add_u64 v[196:197], s[56:57], 0, v[130:131]
	s_mov_b32 m0, s85
	ds_read_b128 v[184:187], v173 offset:16384
	ds_read_b128 v[188:191], v173 offset:17408
	ds_read_b128 v[192:195], v173 offset:18432
	ds_read_b128 v[200:203], v173 offset:19456
	ds_read_b128 v[204:207], v173 offset:20480
	ds_read_b128 v[208:211], v173 offset:21504
	ds_read_b128 v[212:215], v173 offset:22528
	ds_read_b128 v[216:219], v173 offset:23552
	global_load_lds_dwordx4 v[196:197], off
	s_add_i32 m0, s85, 0x2000
	s_add_u32 s86, s56, 0xb0000
	v_lshl_add_u64 v[220:221], s[56:57], 0, v[134:135]
	s_addc_u32 s87, s57, 0
	s_add_i32 s85, s79, s16
	global_load_lds_dwordx4 v[220:221], off
	v_lshl_add_u64 v[224:225], s[86:87], 0, v[130:131]
	s_mov_b32 m0, s85
	v_lshl_add_u64 v[226:227], s[58:59], 0, v[132:133]
	global_load_lds_dwordx4 v[224:225], off
	v_lshl_add_u64 v[224:225], s[86:87], 0, v[134:135]
	s_add_i32 m0, s85, 0x2000
	s_nop 0
	global_load_lds_dwordx4 v[224:225], off
	v_lshl_add_u64 v[224:225], s[58:59], 0, v[128:129]
	s_mov_b32 m0, s17
	s_nop 0
	global_load_lds_dwordx4 v[224:225], off
	s_mov_b32 m0, s39
	s_nop 0
	global_load_lds_dwordx4 v[226:227], off
	s_waitcnt vmcnt(8)
	s_waitcnt lgkmcnt(0)
	s_barrier
	s_setprio 1
	s_waitcnt lgkmcnt(0)
	v_mfma_f32_16x16x32_bf16 v[60:63], v[144:147], v[184:187], v[60:63]
	v_mfma_f32_16x16x32_bf16 v[56:59], v[152:155], v[184:187], v[56:59]
	v_mfma_f32_16x16x32_bf16 v[44:47], v[144:147], v[192:195], v[44:47]
	v_mfma_f32_16x16x32_bf16 v[40:43], v[152:155], v[192:195], v[40:43]
	v_mfma_f32_16x16x32_bf16 v[28:31], v[144:147], v[204:207], v[28:31]
	v_mfma_f32_16x16x32_bf16 v[24:27], v[152:155], v[204:207], v[24:27]
	v_mfma_f32_16x16x32_bf16 v[12:15], v[144:147], v[212:215], v[12:15]
	v_mfma_f32_16x16x32_bf16 v[8:11], v[152:155], v[212:215], v[8:11]
	v_mfma_f32_16x16x32_bf16 v[60:63], v[148:151], v[188:191], v[60:63]
	v_mfma_f32_16x16x32_bf16 v[56:59], v[156:159], v[188:191], v[56:59]
	v_mfma_f32_16x16x32_bf16 v[44:47], v[148:151], v[200:203], v[44:47]
	v_mfma_f32_16x16x32_bf16 v[40:43], v[156:159], v[200:203], v[40:43]
	v_mfma_f32_16x16x32_bf16 v[28:31], v[148:151], v[208:211], v[28:31]
	v_mfma_f32_16x16x32_bf16 v[24:27], v[156:159], v[208:211], v[24:27]
	v_mfma_f32_16x16x32_bf16 v[12:15], v[148:151], v[216:219], v[12:15]
	v_mfma_f32_16x16x32_bf16 v[8:11], v[156:159], v[216:219], v[8:11]
	v_mfma_f32_16x16x32_bf16 v[52:55], v[160:163], v[184:187], v[52:55]
	v_mfma_f32_16x16x32_bf16 v[48:51], v[176:179], v[184:187], v[48:51]
	v_mfma_f32_16x16x32_bf16 v[36:39], v[160:163], v[192:195], v[36:39]
	v_mfma_f32_16x16x32_bf16 v[32:35], v[176:179], v[192:195], v[32:35]
	v_mfma_f32_16x16x32_bf16 v[20:23], v[160:163], v[204:207], v[20:23]
	v_mfma_f32_16x16x32_bf16 v[16:19], v[176:179], v[204:207], v[16:19]
	v_mfma_f32_16x16x32_bf16 v[4:7], v[160:163], v[212:215], v[4:7]
	v_mfma_f32_16x16x32_bf16 v[0:3], v[176:179], v[212:215], v[0:3]
	v_mfma_f32_16x16x32_bf16 v[52:55], v[164:167], v[188:191], v[52:55]
	v_mfma_f32_16x16x32_bf16 v[48:51], v[180:183], v[188:191], v[48:51]
	v_mfma_f32_16x16x32_bf16 v[36:39], v[164:167], v[200:203], v[36:39]
	v_mfma_f32_16x16x32_bf16 v[32:35], v[180:183], v[200:203], v[32:35]
	v_mfma_f32_16x16x32_bf16 v[20:23], v[164:167], v[208:211], v[20:23]
	v_mfma_f32_16x16x32_bf16 v[16:19], v[180:183], v[208:211], v[16:19]
	v_mfma_f32_16x16x32_bf16 v[4:7], v[164:167], v[216:219], v[4:7]
	v_mfma_f32_16x16x32_bf16 v[0:3], v[180:183], v[216:219], v[0:3]
	s_setprio 0
	s_barrier
	s_add_i32 s85, 0, 0x18000
	s_add_i32 s86, 0, 0x1c000
	v_add_u32_e32 v156, s85, v169
	v_add_u32_e32 v175, s86, v169
	ds_read_b128 v[144:147], v156
	ds_read_b128 v[148:151], v156 offset:1024
	ds_read_b128 v[152:155], v156 offset:2048
	ds_read_b128 v[156:159], v156 offset:3072
	ds_read_b128 v[160:163], v175
	ds_read_b128 v[164:167], v175 offset:1024
	ds_read_b128 v[176:179], v175 offset:2048
	ds_read_b128 v[180:183], v175 offset:3072
	s_add_u32 s58, s58, 0xb0000
	s_addc_u32 s59, s59, 0
	s_mov_b32 m0, s45
	v_lshl_add_u64 v[228:229], s[58:59], 0, v[128:129]
	ds_read_b128 v[184:187], v173 offset:32768
	ds_read_b128 v[188:191], v173 offset:33792
	ds_read_b128 v[192:195], v173 offset:34816
	ds_read_b128 v[200:203], v173 offset:35840
	ds_read_b128 v[204:207], v173 offset:36864
	ds_read_b128 v[208:211], v173 offset:37888
	ds_read_b128 v[212:215], v173 offset:38912
	ds_read_b128 v[216:219], v173 offset:39936
	global_load_lds_dwordx4 v[228:229], off
	v_lshl_add_u64 v[228:229], s[58:59], 0, v[132:133]
	s_mov_b32 m0, s60
	s_nop 0
	global_load_lds_dwordx4 v[228:229], off
	s_waitcnt vmcnt(8)
	s_waitcnt lgkmcnt(0)
	s_barrier
	s_setprio 1
	s_waitcnt lgkmcnt(0)
	v_mfma_f32_16x16x32_bf16 v[124:127], v[144:147], v[184:187], v[124:127]
	v_mfma_f32_16x16x32_bf16 v[120:123], v[152:155], v[184:187], v[120:123]
	v_mfma_f32_16x16x32_bf16 v[108:111], v[144:147], v[192:195], v[108:111]
	v_mfma_f32_16x16x32_bf16 v[104:107], v[152:155], v[192:195], v[104:107]
	v_mfma_f32_16x16x32_bf16 v[92:95], v[144:147], v[204:207], v[92:95]
	v_mfma_f32_16x16x32_bf16 v[88:91], v[152:155], v[204:207], v[88:91]
	v_mfma_f32_16x16x32_bf16 v[76:79], v[144:147], v[212:215], v[76:79]
	v_mfma_f32_16x16x32_bf16 v[72:75], v[152:155], v[212:215], v[72:75]
	v_mfma_f32_16x16x32_bf16 v[124:127], v[148:151], v[188:191], v[124:127]
	v_mfma_f32_16x16x32_bf16 v[120:123], v[156:159], v[188:191], v[120:123]
	v_mfma_f32_16x16x32_bf16 v[108:111], v[148:151], v[200:203], v[108:111]
	v_mfma_f32_16x16x32_bf16 v[104:107], v[156:159], v[200:203], v[104:107]
	v_mfma_f32_16x16x32_bf16 v[92:95], v[148:151], v[208:211], v[92:95]
	v_mfma_f32_16x16x32_bf16 v[88:91], v[156:159], v[208:211], v[88:91]
	v_mfma_f32_16x16x32_bf16 v[76:79], v[148:151], v[216:219], v[76:79]
	v_mfma_f32_16x16x32_bf16 v[72:75], v[156:159], v[216:219], v[72:75]
	v_mfma_f32_16x16x32_bf16 v[116:119], v[160:163], v[184:187], v[116:119]
	v_mfma_f32_16x16x32_bf16 v[112:115], v[176:179], v[184:187], v[112:115]
	v_mfma_f32_16x16x32_bf16 v[100:103], v[160:163], v[192:195], v[100:103]
	v_mfma_f32_16x16x32_bf16 v[96:99], v[176:179], v[192:195], v[96:99]
	v_mfma_f32_16x16x32_bf16 v[84:87], v[160:163], v[204:207], v[84:87]
	v_mfma_f32_16x16x32_bf16 v[80:83], v[176:179], v[204:207], v[80:83]
	v_mfma_f32_16x16x32_bf16 v[68:71], v[160:163], v[212:215], v[68:71]
	v_mfma_f32_16x16x32_bf16 v[64:67], v[176:179], v[212:215], v[64:67]
	v_mfma_f32_16x16x32_bf16 v[116:119], v[164:167], v[188:191], v[116:119]
	v_mfma_f32_16x16x32_bf16 v[112:115], v[180:183], v[188:191], v[112:115]
	v_mfma_f32_16x16x32_bf16 v[100:103], v[164:167], v[200:203], v[100:103]
	v_mfma_f32_16x16x32_bf16 v[96:99], v[180:183], v[200:203], v[96:99]
	v_mfma_f32_16x16x32_bf16 v[84:87], v[164:167], v[208:211], v[84:87]
	v_mfma_f32_16x16x32_bf16 v[80:83], v[180:183], v[208:211], v[80:83]
	v_mfma_f32_16x16x32_bf16 v[68:71], v[164:167], v[216:219], v[68:71]
	v_mfma_f32_16x16x32_bf16 v[64:67], v[180:183], v[216:219], v[64:67]
	s_setprio 0
	s_barrier
	s_add_i32 s58, s85, s16
	v_lshl_add_u64 v[196:197], v[196:197], 0, s[18:19]
	s_mov_b32 m0, s58
	ds_read_b128 v[184:187], v173 offset:49152
	ds_read_b128 v[188:191], v173 offset:50176
	ds_read_b128 v[192:195], v173 offset:51200
	ds_read_b128 v[200:203], v173 offset:52224
	ds_read_b128 v[204:207], v173 offset:53248
	ds_read_b128 v[208:211], v173 offset:54272
	ds_read_b128 v[212:215], v173 offset:55296
	ds_read_b128 v[216:219], v173 offset:56320
	global_load_lds_dwordx4 v[196:197], off
	s_add_i32 m0, s58, 0x2000
	s_add_u32 s56, s56, 0xb0080
	v_lshl_add_u64 v[196:197], v[220:221], 0, s[18:19]
	s_addc_u32 s57, s57, 0
	s_add_i32 s58, s86, s16
	global_load_lds_dwordx4 v[196:197], off
	v_lshl_add_u64 v[196:197], s[56:57], 0, v[130:131]
	s_mov_b32 m0, s58
	s_nop 0
	global_load_lds_dwordx4 v[196:197], off
	v_lshl_add_u64 v[196:197], s[56:57], 0, v[134:135]
	s_add_i32 m0, s58, 0x2000
	s_nop 0
	global_load_lds_dwordx4 v[196:197], off
	v_lshl_add_u64 v[196:197], v[224:225], 0, s[18:19]
	s_mov_b32 m0, s67
	s_nop 0
	global_load_lds_dwordx4 v[196:197], off
	v_lshl_add_u64 v[196:197], v[226:227], 0, s[18:19]
	s_mov_b32 m0, s70
	s_nop 0
	global_load_lds_dwordx4 v[196:197], off
	s_waitcnt vmcnt(8)
	s_waitcnt lgkmcnt(0)
	s_barrier
	s_setprio 1
	s_waitcnt lgkmcnt(0)
	v_mfma_f32_16x16x32_bf16 v[60:63], v[144:147], v[184:187], v[60:63]
	v_mfma_f32_16x16x32_bf16 v[56:59], v[152:155], v[184:187], v[56:59]
	v_mfma_f32_16x16x32_bf16 v[44:47], v[144:147], v[192:195], v[44:47]
	v_mfma_f32_16x16x32_bf16 v[40:43], v[152:155], v[192:195], v[40:43]
	v_mfma_f32_16x16x32_bf16 v[28:31], v[144:147], v[204:207], v[28:31]
	v_mfma_f32_16x16x32_bf16 v[24:27], v[152:155], v[204:207], v[24:27]
	v_mfma_f32_16x16x32_bf16 v[12:15], v[144:147], v[212:215], v[12:15]
	v_mfma_f32_16x16x32_bf16 v[8:11], v[152:155], v[212:215], v[8:11]
	v_mfma_f32_16x16x32_bf16 v[60:63], v[148:151], v[188:191], v[60:63]
	v_mfma_f32_16x16x32_bf16 v[56:59], v[156:159], v[188:191], v[56:59]
	v_mfma_f32_16x16x32_bf16 v[44:47], v[148:151], v[200:203], v[44:47]
	v_mfma_f32_16x16x32_bf16 v[40:43], v[156:159], v[200:203], v[40:43]
	v_mfma_f32_16x16x32_bf16 v[28:31], v[148:151], v[208:211], v[28:31]
	v_mfma_f32_16x16x32_bf16 v[24:27], v[156:159], v[208:211], v[24:27]
	v_mfma_f32_16x16x32_bf16 v[12:15], v[148:151], v[216:219], v[12:15]
	v_mfma_f32_16x16x32_bf16 v[8:11], v[156:159], v[216:219], v[8:11]
	v_mfma_f32_16x16x32_bf16 v[52:55], v[160:163], v[184:187], v[52:55]
	v_mfma_f32_16x16x32_bf16 v[48:51], v[176:179], v[184:187], v[48:51]
	v_mfma_f32_16x16x32_bf16 v[36:39], v[160:163], v[192:195], v[36:39]
	v_mfma_f32_16x16x32_bf16 v[32:35], v[176:179], v[192:195], v[32:35]
	v_mfma_f32_16x16x32_bf16 v[20:23], v[160:163], v[204:207], v[20:23]
	v_mfma_f32_16x16x32_bf16 v[16:19], v[176:179], v[204:207], v[16:19]
	v_mfma_f32_16x16x32_bf16 v[4:7], v[160:163], v[212:215], v[4:7]
	v_mfma_f32_16x16x32_bf16 v[0:3], v[176:179], v[212:215], v[0:3]
	v_mfma_f32_16x16x32_bf16 v[52:55], v[164:167], v[188:191], v[52:55]
	v_mfma_f32_16x16x32_bf16 v[48:51], v[180:183], v[188:191], v[48:51]
	v_mfma_f32_16x16x32_bf16 v[36:39], v[164:167], v[200:203], v[36:39]
	v_mfma_f32_16x16x32_bf16 v[32:35], v[180:183], v[200:203], v[32:35]
	v_mfma_f32_16x16x32_bf16 v[20:23], v[164:167], v[208:211], v[20:23]
	v_mfma_f32_16x16x32_bf16 v[16:19], v[180:183], v[208:211], v[16:19]
	v_mfma_f32_16x16x32_bf16 v[4:7], v[164:167], v[216:219], v[4:7]
	v_mfma_f32_16x16x32_bf16 v[0:3], v[180:183], v[216:219], v[0:3]
	s_setprio 0
	s_barrier
	s_add_i32 s84, s84, 2
	s_add_u32 s54, s54, 0x100
	s_addc_u32 s55, s55, 0
	s_add_u32 s82, s82, 0x100
	s_addc_u32 s83, s83, 0
	s_cmp_gt_u32 s84, 41
	s_cbranch_scc0 .LBB0_340
	s_and_b64 vcc, exec, s[20:21]
	s_cbranch_vccz .LBB0_343
	s_barrier

.LBB0_476:
	v_add_u32_e32 v164, s71, v188
	ds_read_b128 v[128:131], v210
	ds_read_b128 v[132:135], v210 offset:1024
	ds_read_b128 v[136:139], v210 offset:2048
	ds_read_b128 v[140:143], v210 offset:3072
	ds_read_b128 v[144:147], v164
	ds_read_b128 v[148:151], v164 offset:1024
	ds_read_b128 v[152:155], v164 offset:2048
	ds_read_b128 v[178:181], v164 offset:3072
	s_add_u32 s6, s4, 0xfffc0080
	s_addc_u32 s7, s5, -1
	s_cmp_eq_u32 s91, 12
	s_cselect_b32 s13, s10, s7
	s_cselect_b32 s12, s11, s6
	s_cselect_b32 s7, s20, s90
	s_cselect_b32 s6, s83, s85
	v_lshl_add_u64 v[186:187], s[4:5], 0, v[174:175]
	s_add_i32 m0, s25, 0xc000
	ds_read_b128 v[182:185], v206
	ds_read_b128 v[218:221], v206 offset:1024
	ds_read_b128 v[224:227], v206 offset:2048
	ds_read_b128 v[228:231], v206 offset:3072
	ds_read_b128 v[232:235], v206 offset:4096
	ds_read_b128 v[236:239], v206 offset:5120
	ds_read_b128 v[240:243], v206 offset:6144
	ds_read_b128 v[244:247], v206 offset:7168
	global_load_lds_dwordx4 v[186:187], off
	v_lshl_add_u64 v[186:187], s[4:5], 0, v[176:177]
	s_add_i32 m0, s25, 0xe000
	s_nop 0
	global_load_lds_dwordx4 v[186:187], off
	s_waitcnt vmcnt(8)
	s_waitcnt lgkmcnt(0)
	s_barrier
	s_setprio 1
	s_waitcnt lgkmcnt(0)
	v_mfma_f32_16x16x32_bf16 v[112:115], v[128:131], v[182:185], v[112:115]
	v_mfma_f32_16x16x32_bf16 v[116:119], v[136:139], v[182:185], v[116:119]
	v_mfma_f32_16x16x32_bf16 v[80:83], v[128:131], v[224:227], v[80:83]
	v_mfma_f32_16x16x32_bf16 v[88:91], v[136:139], v[224:227], v[88:91]
	v_mfma_f32_16x16x32_bf16 v[64:67], v[128:131], v[232:235], v[64:67]
	v_mfma_f32_16x16x32_bf16 v[68:71], v[136:139], v[232:235], v[68:71]
	v_mfma_f32_16x16x32_bf16 v[48:51], v[128:131], v[240:243], v[48:51]
	v_mfma_f32_16x16x32_bf16 v[52:55], v[136:139], v[240:243], v[52:55]
	v_mfma_f32_16x16x32_bf16 v[112:115], v[132:135], v[218:221], v[112:115]
	v_mfma_f32_16x16x32_bf16 v[116:119], v[140:143], v[218:221], v[116:119]
	v_mfma_f32_16x16x32_bf16 v[80:83], v[132:135], v[228:231], v[80:83]
	v_mfma_f32_16x16x32_bf16 v[88:91], v[140:143], v[228:231], v[88:91]
	v_mfma_f32_16x16x32_bf16 v[64:67], v[132:135], v[236:239], v[64:67]
	v_mfma_f32_16x16x32_bf16 v[68:71], v[140:143], v[236:239], v[68:71]
	v_mfma_f32_16x16x32_bf16 v[48:51], v[132:135], v[244:247], v[48:51]
	v_mfma_f32_16x16x32_bf16 v[52:55], v[140:143], v[244:247], v[52:55]
	v_mfma_f32_16x16x32_bf16 v[120:123], v[144:147], v[182:185], v[120:123]
	v_mfma_f32_16x16x32_bf16 v[124:127], v[152:155], v[182:185], v[124:127]
	v_mfma_f32_16x16x32_bf16 v[96:99], v[144:147], v[224:227], v[96:99]
	v_mfma_f32_16x16x32_bf16 v[104:107], v[152:155], v[224:227], v[104:107]
	v_mfma_f32_16x16x32_bf16 v[72:75], v[144:147], v[232:235], v[72:75]
	v_mfma_f32_16x16x32_bf16 v[76:79], v[152:155], v[232:235], v[76:79]
	v_mfma_f32_16x16x32_bf16 v[56:59], v[144:147], v[240:243], v[56:59]
	v_mfma_f32_16x16x32_bf16 v[60:63], v[152:155], v[240:243], v[60:63]
	v_mfma_f32_16x16x32_bf16 v[120:123], v[148:151], v[218:221], v[120:123]
	v_mfma_f32_16x16x32_bf16 v[124:127], v[178:181], v[218:221], v[124:127]
	v_mfma_f32_16x16x32_bf16 v[96:99], v[148:151], v[228:231], v[96:99]
	v_mfma_f32_16x16x32_bf16 v[104:107], v[178:181], v[228:231], v[104:107]
	v_mfma_f32_16x16x32_bf16 v[72:75], v[148:151], v[236:239], v[72:75]
	v_mfma_f32_16x16x32_bf16 v[76:79], v[178:181], v[236:239], v[76:79]
	v_mfma_f32_16x16x32_bf16 v[56:59], v[148:151], v[244:247], v[56:59]
	v_mfma_f32_16x16x32_bf16 v[60:63], v[178:181], v[244:247], v[60:63]
	s_setprio 0
	s_barrier
	s_add_i32 s92, s70, s62
	v_lshl_add_u64 v[186:187], s[6:7], 0, v[158:159]
	s_mov_b32 m0, s92
	ds_read_b128 v[182:185], v206 offset:16384
	ds_read_b128 v[218:221], v206 offset:17408
	ds_read_b128 v[224:227], v206 offset:18432
	ds_read_b128 v[228:231], v206 offset:19456
	ds_read_b128 v[232:235], v206 offset:20480
	ds_read_b128 v[236:239], v206 offset:21504
	ds_read_b128 v[240:243], v206 offset:22528
	ds_read_b128 v[244:247], v206 offset:23552
	global_load_lds_dwordx4 v[186:187], off
	s_add_i32 m0, s92, 0x2000
	s_add_u32 s92, s6, 0x40000
	v_lshl_add_u64 v[248:249], s[6:7], 0, v[162:163]
	s_addc_u32 s93, s7, 0
	s_add_i32 s94, s71, s62
	global_load_lds_dwordx4 v[248:249], off
	v_lshl_add_u64 v[250:251], s[92:93], 0, v[158:159]
	s_mov_b32 m0, s94
	v_lshl_add_u64 v[252:253], s[12:13], 0, v[160:161]
	global_load_lds_dwordx4 v[250:251], off
	v_lshl_add_u64 v[250:251], s[92:93], 0, v[162:163]
	s_add_i32 m0, s94, 0x2000
	s_nop 0
	global_load_lds_dwordx4 v[250:251], off
	v_lshl_add_u64 v[250:251], s[12:13], 0, v[156:157]
	s_mov_b32 m0, s25
	s_nop 0
	global_load_lds_dwordx4 v[250:251], off
	s_mov_b32 m0, s63
	s_nop 0
	global_load_lds_dwordx4 v[252:253], off
	s_waitcnt vmcnt(8)
	s_waitcnt lgkmcnt(0)
	s_barrier
	s_setprio 1
	s_waitcnt lgkmcnt(0)
	v_mfma_f32_16x16x32_bf16 v[32:35], v[128:131], v[182:185], v[32:35]
	v_mfma_f32_16x16x32_bf16 v[36:39], v[136:139], v[182:185], v[36:39]
	v_mfma_f32_16x16x32_bf16 v[16:19], v[128:131], v[224:227], v[16:19]
	v_mfma_f32_16x16x32_bf16 v[20:23], v[136:139], v[224:227], v[20:23]
	v_mfma_f32_16x16x32_bf16 v[0:3], v[128:131], v[232:235], v[0:3]
	v_mfma_f32_16x16x32_bf16 v[4:7], v[136:139], v[232:235], v[4:7]
	v_mfma_f32_16x16x32_bf16 v[84:87], v[128:131], v[240:243], v[84:87]
	v_mfma_f32_16x16x32_bf16 v[92:95], v[136:139], v[240:243], v[92:95]
	v_mfma_f32_16x16x32_bf16 v[32:35], v[132:135], v[218:221], v[32:35]
	v_mfma_f32_16x16x32_bf16 v[36:39], v[140:143], v[218:221], v[36:39]
	v_mfma_f32_16x16x32_bf16 v[16:19], v[132:135], v[228:231], v[16:19]
	v_mfma_f32_16x16x32_bf16 v[20:23], v[140:143], v[228:231], v[20:23]
	v_mfma_f32_16x16x32_bf16 v[0:3], v[132:135], v[236:239], v[0:3]
	v_mfma_f32_16x16x32_bf16 v[4:7], v[140:143], v[236:239], v[4:7]
	v_mfma_f32_16x16x32_bf16 v[84:87], v[132:135], v[244:247], v[84:87]
	v_mfma_f32_16x16x32_bf16 v[92:95], v[140:143], v[244:247], v[92:95]
	v_mfma_f32_16x16x32_bf16 v[40:43], v[144:147], v[182:185], v[40:43]
	v_mfma_f32_16x16x32_bf16 v[44:47], v[152:155], v[182:185], v[44:47]
	v_mfma_f32_16x16x32_bf16 v[24:27], v[144:147], v[224:227], v[24:27]
	v_mfma_f32_16x16x32_bf16 v[28:31], v[152:155], v[224:227], v[28:31]
	v_mfma_f32_16x16x32_bf16 v[8:11], v[144:147], v[232:235], v[8:11]
	v_mfma_f32_16x16x32_bf16 v[12:15], v[152:155], v[232:235], v[12:15]
	v_mfma_f32_16x16x32_bf16 v[100:103], v[144:147], v[240:243], v[100:103]
	v_mfma_f32_16x16x32_bf16 v[108:111], v[152:155], v[240:243], v[108:111]
	v_mfma_f32_16x16x32_bf16 v[40:43], v[148:151], v[218:221], v[40:43]
	v_mfma_f32_16x16x32_bf16 v[44:47], v[178:181], v[218:221], v[44:47]
	v_mfma_f32_16x16x32_bf16 v[24:27], v[148:151], v[228:231], v[24:27]
	v_mfma_f32_16x16x32_bf16 v[28:31], v[178:181], v[228:231], v[28:31]
	v_mfma_f32_16x16x32_bf16 v[8:11], v[148:151], v[236:239], v[8:11]
	v_mfma_f32_16x16x32_bf16 v[12:15], v[178:181], v[236:239], v[12:15]
	v_mfma_f32_16x16x32_bf16 v[100:103], v[148:151], v[244:247], v[100:103]
	v_mfma_f32_16x16x32_bf16 v[108:111], v[178:181], v[244:247], v[108:111]
	s_setprio 0
	s_barrier
	s_add_i32 s92, 0, 0x18000
	s_add_i32 s93, 0, 0x1c000
	v_add_u32_e32 v140, s92, v188
	v_add_u32_e32 v164, s93, v188
	ds_read_b128 v[128:131], v140
	ds_read_b128 v[132:135], v140 offset:1024
	ds_read_b128 v[136:139], v140 offset:2048
	ds_read_b128 v[140:143], v140 offset:3072
	ds_read_b128 v[144:147], v164
	ds_read_b128 v[148:151], v164 offset:1024
	ds_read_b128 v[152:155], v164 offset:2048
	ds_read_b128 v[178:181], v164 offset:3072
	s_add_u32 s12, s12, 0x40000
	s_addc_u32 s13, s13, 0
	s_mov_b32 m0, s64
	v_lshl_add_u64 v[200:201], s[12:13], 0, v[156:157]
	ds_read_b128 v[182:185], v206 offset:32768
	ds_read_b128 v[218:221], v206 offset:33792
	ds_read_b128 v[224:227], v206 offset:34816
	ds_read_b128 v[228:231], v206 offset:35840
	ds_read_b128 v[232:235], v206 offset:36864
	ds_read_b128 v[236:239], v206 offset:37888
	ds_read_b128 v[240:243], v206 offset:38912
	ds_read_b128 v[244:247], v206 offset:39936
	global_load_lds_dwordx4 v[200:201], off
	v_lshl_add_u64 v[200:201], s[12:13], 0, v[160:161]
	s_mov_b32 m0, s65
	s_nop 0
	global_load_lds_dwordx4 v[200:201], off
	s_waitcnt vmcnt(8)
	s_waitcnt lgkmcnt(0)
	s_barrier
	s_setprio 1
	s_waitcnt lgkmcnt(0)
	v_mfma_f32_16x16x32_bf16 v[112:115], v[128:131], v[182:185], v[112:115]
	v_mfma_f32_16x16x32_bf16 v[116:119], v[136:139], v[182:185], v[116:119]
	v_mfma_f32_16x16x32_bf16 v[80:83], v[128:131], v[224:227], v[80:83]
	v_mfma_f32_16x16x32_bf16 v[88:91], v[136:139], v[224:227], v[88:91]
	v_mfma_f32_16x16x32_bf16 v[64:67], v[128:131], v[232:235], v[64:67]
	v_mfma_f32_16x16x32_bf16 v[68:71], v[136:139], v[232:235], v[68:71]
	v_mfma_f32_16x16x32_bf16 v[48:51], v[128:131], v[240:243], v[48:51]
	v_mfma_f32_16x16x32_bf16 v[52:55], v[136:139], v[240:243], v[52:55]
	v_mfma_f32_16x16x32_bf16 v[112:115], v[132:135], v[218:221], v[112:115]
	v_mfma_f32_16x16x32_bf16 v[116:119], v[140:143], v[218:221], v[116:119]
	v_mfma_f32_16x16x32_bf16 v[80:83], v[132:135], v[228:231], v[80:83]
	v_mfma_f32_16x16x32_bf16 v[88:91], v[140:143], v[228:231], v[88:91]
	v_mfma_f32_16x16x32_bf16 v[64:67], v[132:135], v[236:239], v[64:67]
	v_mfma_f32_16x16x32_bf16 v[68:71], v[140:143], v[236:239], v[68:71]
	v_mfma_f32_16x16x32_bf16 v[48:51], v[132:135], v[244:247], v[48:51]
	v_mfma_f32_16x16x32_bf16 v[52:55], v[140:143], v[244:247], v[52:55]
	v_mfma_f32_16x16x32_bf16 v[120:123], v[144:147], v[182:185], v[120:123]
	v_mfma_f32_16x16x32_bf16 v[124:127], v[152:155], v[182:185], v[124:127]
	v_mfma_f32_16x16x32_bf16 v[96:99], v[144:147], v[224:227], v[96:99]
	v_mfma_f32_16x16x32_bf16 v[104:107], v[152:155], v[224:227], v[104:107]
	v_mfma_f32_16x16x32_bf16 v[72:75], v[144:147], v[232:235], v[72:75]
	v_mfma_f32_16x16x32_bf16 v[76:79], v[152:155], v[232:235], v[76:79]
	v_mfma_f32_16x16x32_bf16 v[56:59], v[144:147], v[240:243], v[56:59]
	v_mfma_f32_16x16x32_bf16 v[60:63], v[152:155], v[240:243], v[60:63]
	v_mfma_f32_16x16x32_bf16 v[120:123], v[148:151], v[218:221], v[120:123]
	v_mfma_f32_16x16x32_bf16 v[124:127], v[178:181], v[218:221], v[124:127]
	v_mfma_f32_16x16x32_bf16 v[96:99], v[148:151], v[228:231], v[96:99]
	v_mfma_f32_16x16x32_bf16 v[104:107], v[178:181], v[228:231], v[104:107]
	v_mfma_f32_16x16x32_bf16 v[72:75], v[148:151], v[236:239], v[72:75]
	v_mfma_f32_16x16x32_bf16 v[76:79], v[178:181], v[236:239], v[76:79]
	v_mfma_f32_16x16x32_bf16 v[56:59], v[148:151], v[244:247], v[56:59]
	v_mfma_f32_16x16x32_bf16 v[60:63], v[178:181], v[244:247], v[60:63]
	s_setprio 0
	s_barrier
	s_add_i32 s12, s92, s62
	v_lshl_add_u64 v[186:187], v[186:187], 0, s[50:51]
	s_mov_b32 m0, s12
	ds_read_b128 v[182:185], v206 offset:49152
	ds_read_b128 v[218:221], v206 offset:50176
	ds_read_b128 v[224:227], v206 offset:51200
	ds_read_b128 v[228:231], v206 offset:52224
	ds_read_b128 v[232:235], v206 offset:53248
	ds_read_b128 v[236:239], v206 offset:54272
	ds_read_b128 v[240:243], v206 offset:55296
	ds_read_b128 v[244:247], v206 offset:56320
	global_load_lds_dwordx4 v[186:187], off
	s_add_i32 m0, s12, 0x2000
	s_add_u32 s6, s6, 0x40080
	v_lshl_add_u64 v[186:187], v[248:249], 0, s[50:51]
	s_addc_u32 s7, s7, 0
	s_add_i32 s12, s93, s62
	global_load_lds_dwordx4 v[186:187], off
	v_lshl_add_u64 v[186:187], s[6:7], 0, v[158:159]
	s_mov_b32 m0, s12
	s_nop 0
	global_load_lds_dwordx4 v[186:187], off
	v_lshl_add_u64 v[186:187], s[6:7], 0, v[162:163]
	s_add_i32 m0, s12, 0x2000
	s_nop 0
	global_load_lds_dwordx4 v[186:187], off
	v_lshl_add_u64 v[186:187], v[250:251], 0, s[50:51]
	s_mov_b32 m0, s78
	s_nop 0
	global_load_lds_dwordx4 v[186:187], off
	v_lshl_add_u64 v[186:187], v[252:253], 0, s[50:51]
	s_mov_b32 m0, s79
	s_nop 0
	global_load_lds_dwordx4 v[186:187], off
	s_waitcnt vmcnt(8)
	s_waitcnt lgkmcnt(0)
	s_barrier
	s_setprio 1
	s_waitcnt lgkmcnt(0)
	v_mfma_f32_16x16x32_bf16 v[32:35], v[128:131], v[182:185], v[32:35]
	v_mfma_f32_16x16x32_bf16 v[36:39], v[136:139], v[182:185], v[36:39]
	v_mfma_f32_16x16x32_bf16 v[16:19], v[128:131], v[224:227], v[16:19]
	v_mfma_f32_16x16x32_bf16 v[20:23], v[136:139], v[224:227], v[20:23]
	v_mfma_f32_16x16x32_bf16 v[0:3], v[128:131], v[232:235], v[0:3]
	v_mfma_f32_16x16x32_bf16 v[4:7], v[136:139], v[232:235], v[4:7]
	v_mfma_f32_16x16x32_bf16 v[84:87], v[128:131], v[240:243], v[84:87]
	v_mfma_f32_16x16x32_bf16 v[92:95], v[136:139], v[240:243], v[92:95]
	v_mfma_f32_16x16x32_bf16 v[32:35], v[132:135], v[218:221], v[32:35]
	v_mfma_f32_16x16x32_bf16 v[36:39], v[140:143], v[218:221], v[36:39]
	v_mfma_f32_16x16x32_bf16 v[16:19], v[132:135], v[228:231], v[16:19]
	v_mfma_f32_16x16x32_bf16 v[20:23], v[140:143], v[228:231], v[20:23]
	v_mfma_f32_16x16x32_bf16 v[0:3], v[132:135], v[236:239], v[0:3]
	v_mfma_f32_16x16x32_bf16 v[4:7], v[140:143], v[236:239], v[4:7]
	v_mfma_f32_16x16x32_bf16 v[84:87], v[132:135], v[244:247], v[84:87]
	v_mfma_f32_16x16x32_bf16 v[92:95], v[140:143], v[244:247], v[92:95]
	v_mfma_f32_16x16x32_bf16 v[40:43], v[144:147], v[182:185], v[40:43]
	v_mfma_f32_16x16x32_bf16 v[44:47], v[152:155], v[182:185], v[44:47]
	v_mfma_f32_16x16x32_bf16 v[24:27], v[144:147], v[224:227], v[24:27]
	v_mfma_f32_16x16x32_bf16 v[28:31], v[152:155], v[224:227], v[28:31]
	v_mfma_f32_16x16x32_bf16 v[8:11], v[144:147], v[232:235], v[8:11]
	v_mfma_f32_16x16x32_bf16 v[12:15], v[152:155], v[232:235], v[12:15]
	v_mfma_f32_16x16x32_bf16 v[100:103], v[144:147], v[240:243], v[100:103]
	v_mfma_f32_16x16x32_bf16 v[108:111], v[152:155], v[240:243], v[108:111]
	v_mfma_f32_16x16x32_bf16 v[40:43], v[148:151], v[218:221], v[40:43]
	v_mfma_f32_16x16x32_bf16 v[44:47], v[178:181], v[218:221], v[44:47]
	v_mfma_f32_16x16x32_bf16 v[24:27], v[148:151], v[228:231], v[24:27]
	v_mfma_f32_16x16x32_bf16 v[28:31], v[178:181], v[228:231], v[28:31]
	v_mfma_f32_16x16x32_bf16 v[8:11], v[148:151], v[236:239], v[8:11]
	v_mfma_f32_16x16x32_bf16 v[12:15], v[178:181], v[236:239], v[12:15]
	v_mfma_f32_16x16x32_bf16 v[100:103], v[148:151], v[244:247], v[100:103]
	v_mfma_f32_16x16x32_bf16 v[108:111], v[178:181], v[244:247], v[108:111]
	s_setprio 0
	s_barrier
	s_add_i32 s91, s91, 2
	s_add_u32 s4, s4, 0x100
	s_addc_u32 s5, s5, 0
	s_add_u32 s85, s85, 0x100
	s_addc_u32 s90, s90, 0
	s_cmp_gt_u32 s91, 13
	s_cbranch_scc0 .LBB0_476
	s_and_b64 vcc, exec, s[52:53]
	s_cbranch_vccz .LBB0_479
	s_barrier

.LBB0_1471:
	ds_read_b128 v[144:147], v159
	ds_read_b128 v[162:165], v159 offset:1024
	ds_read_b128 v[166:169], v159 offset:2048
	ds_read_b128 v[170:173], v159 offset:3072
	ds_read_b128 v[174:177], v160
	ds_read_b128 v[178:181], v160 offset:1024
	ds_read_b128 v[182:185], v160 offset:2048
	ds_read_b128 v[186:189], v160 offset:3072
	s_add_u32 s46, s44, 0xfffe0080
	s_addc_u32 s47, s45, -1
	s_cmp_eq_u32 s66, 4
	s_cselect_b32 s49, s10, s47
	s_cselect_b32 s48, s11, s46
	s_cselect_b32 s47, s19, s65
	s_cselect_b32 s46, s21, s64
	v_lshl_add_u64 v[224:225], s[44:45], 0, v[136:137]
	s_add_i32 m0, s43, 0xc000
	ds_read_b128 v[190:193], v161
	ds_read_b128 v[194:197], v161 offset:1024
	ds_read_b128 v[200:203], v161 offset:2048
	ds_read_b128 v[204:207], v161 offset:3072
	ds_read_b128 v[208:211], v161 offset:4096
	ds_read_b128 v[212:215], v161 offset:5120
	ds_read_b128 v[216:219], v161 offset:6144
	ds_read_b128 v[220:223], v161 offset:7168
	global_load_lds_dwordx4 v[224:225], off
	v_lshl_add_u64 v[224:225], s[44:45], 0, v[138:139]
	s_add_i32 m0, s43, 0xe000
	s_nop 0
	global_load_lds_dwordx4 v[224:225], off
	s_waitcnt vmcnt(8)
	s_waitcnt lgkmcnt(0)
	s_barrier
	s_setprio 1
	s_waitcnt lgkmcnt(0)
	v_mfma_f32_16x16x32_bf16 v[124:127], v[144:147], v[190:193], v[124:127]
	v_mfma_f32_16x16x32_bf16 v[120:123], v[166:169], v[190:193], v[120:123]
	v_mfma_f32_16x16x32_bf16 v[108:111], v[144:147], v[200:203], v[108:111]
	v_mfma_f32_16x16x32_bf16 v[104:107], v[166:169], v[200:203], v[104:107]
	v_mfma_f32_16x16x32_bf16 v[92:95], v[144:147], v[208:211], v[92:95]
	v_mfma_f32_16x16x32_bf16 v[88:91], v[166:169], v[208:211], v[88:91]
	v_mfma_f32_16x16x32_bf16 v[76:79], v[144:147], v[216:219], v[76:79]
	v_mfma_f32_16x16x32_bf16 v[72:75], v[166:169], v[216:219], v[72:75]
	v_mfma_f32_16x16x32_bf16 v[124:127], v[162:165], v[194:197], v[124:127]
	v_mfma_f32_16x16x32_bf16 v[120:123], v[170:173], v[194:197], v[120:123]
	v_mfma_f32_16x16x32_bf16 v[108:111], v[162:165], v[204:207], v[108:111]
	v_mfma_f32_16x16x32_bf16 v[104:107], v[170:173], v[204:207], v[104:107]
	v_mfma_f32_16x16x32_bf16 v[92:95], v[162:165], v[212:215], v[92:95]
	v_mfma_f32_16x16x32_bf16 v[88:91], v[170:173], v[212:215], v[88:91]
	v_mfma_f32_16x16x32_bf16 v[76:79], v[162:165], v[220:223], v[76:79]
	v_mfma_f32_16x16x32_bf16 v[72:75], v[170:173], v[220:223], v[72:75]
	v_mfma_f32_16x16x32_bf16 v[116:119], v[174:177], v[190:193], v[116:119]
	v_mfma_f32_16x16x32_bf16 v[112:115], v[182:185], v[190:193], v[112:115]
	v_mfma_f32_16x16x32_bf16 v[100:103], v[174:177], v[200:203], v[100:103]
	v_mfma_f32_16x16x32_bf16 v[96:99], v[182:185], v[200:203], v[96:99]
	v_mfma_f32_16x16x32_bf16 v[84:87], v[174:177], v[208:211], v[84:87]
	v_mfma_f32_16x16x32_bf16 v[80:83], v[182:185], v[208:211], v[80:83]
	v_mfma_f32_16x16x32_bf16 v[68:71], v[174:177], v[216:219], v[68:71]
	v_mfma_f32_16x16x32_bf16 v[64:67], v[182:185], v[216:219], v[64:67]
	v_mfma_f32_16x16x32_bf16 v[116:119], v[178:181], v[194:197], v[116:119]
	v_mfma_f32_16x16x32_bf16 v[112:115], v[186:189], v[194:197], v[112:115]
	v_mfma_f32_16x16x32_bf16 v[100:103], v[178:181], v[204:207], v[100:103]
	v_mfma_f32_16x16x32_bf16 v[96:99], v[186:189], v[204:207], v[96:99]
	v_mfma_f32_16x16x32_bf16 v[84:87], v[178:181], v[212:215], v[84:87]
	v_mfma_f32_16x16x32_bf16 v[80:83], v[186:189], v[212:215], v[80:83]
	v_mfma_f32_16x16x32_bf16 v[68:71], v[178:181], v[220:223], v[68:71]
	v_mfma_f32_16x16x32_bf16 v[64:67], v[186:189], v[220:223], v[64:67]
	s_setprio 0
	s_barrier
	s_add_i32 s67, s61, s52
	v_lshl_add_u64 v[224:225], s[46:47], 0, v[130:131]
	s_mov_b32 m0, s67
	ds_read_b128 v[190:193], v161 offset:16384
	ds_read_b128 v[194:197], v161 offset:17408
	ds_read_b128 v[200:203], v161 offset:18432
	ds_read_b128 v[204:207], v161 offset:19456
	ds_read_b128 v[208:211], v161 offset:20480
	ds_read_b128 v[212:215], v161 offset:21504
	ds_read_b128 v[216:219], v161 offset:22528
	ds_read_b128 v[220:223], v161 offset:23552
	global_load_lds_dwordx4 v[224:225], off
	s_add_i32 m0, s67, 0x2000
	s_add_u32 s70, s46, 0x20000
	v_lshl_add_u64 v[226:227], s[46:47], 0, v[134:135]
	s_addc_u32 s71, s47, 0
	s_add_i32 s67, s62, s52
	global_load_lds_dwordx4 v[226:227], off
	v_lshl_add_u64 v[228:229], s[70:71], 0, v[130:131]
	s_mov_b32 m0, s67
	v_lshl_add_u64 v[230:231], s[48:49], 0, v[132:133]
	global_load_lds_dwordx4 v[228:229], off
	v_lshl_add_u64 v[228:229], s[70:71], 0, v[134:135]
	s_add_i32 m0, s67, 0x2000
	s_nop 0
	global_load_lds_dwordx4 v[228:229], off
	v_lshl_add_u64 v[228:229], s[48:49], 0, v[128:129]
	s_mov_b32 m0, s43
	s_nop 0
	global_load_lds_dwordx4 v[228:229], off
	s_mov_b32 m0, s53
	s_nop 0
	global_load_lds_dwordx4 v[230:231], off
	s_waitcnt vmcnt(8)
	s_waitcnt lgkmcnt(0)
	s_barrier
	s_setprio 1
	s_waitcnt lgkmcnt(0)
	v_mfma_f32_16x16x32_bf16 v[60:63], v[144:147], v[190:193], v[60:63]
	v_mfma_f32_16x16x32_bf16 v[56:59], v[166:169], v[190:193], v[56:59]
	v_mfma_f32_16x16x32_bf16 v[44:47], v[144:147], v[200:203], v[44:47]
	v_mfma_f32_16x16x32_bf16 v[40:43], v[166:169], v[200:203], v[40:43]
	v_mfma_f32_16x16x32_bf16 v[28:31], v[144:147], v[208:211], v[28:31]
	v_mfma_f32_16x16x32_bf16 v[24:27], v[166:169], v[208:211], v[24:27]
	v_mfma_f32_16x16x32_bf16 v[12:15], v[144:147], v[216:219], v[12:15]
	v_mfma_f32_16x16x32_bf16 v[8:11], v[166:169], v[216:219], v[8:11]
	v_mfma_f32_16x16x32_bf16 v[60:63], v[162:165], v[194:197], v[60:63]
	v_mfma_f32_16x16x32_bf16 v[56:59], v[170:173], v[194:197], v[56:59]
	v_mfma_f32_16x16x32_bf16 v[44:47], v[162:165], v[204:207], v[44:47]
	v_mfma_f32_16x16x32_bf16 v[40:43], v[170:173], v[204:207], v[40:43]
	v_mfma_f32_16x16x32_bf16 v[28:31], v[162:165], v[212:215], v[28:31]
	v_mfma_f32_16x16x32_bf16 v[24:27], v[170:173], v[212:215], v[24:27]
	v_mfma_f32_16x16x32_bf16 v[12:15], v[162:165], v[220:223], v[12:15]
	v_mfma_f32_16x16x32_bf16 v[8:11], v[170:173], v[220:223], v[8:11]
	v_mfma_f32_16x16x32_bf16 v[52:55], v[174:177], v[190:193], v[52:55]
	v_mfma_f32_16x16x32_bf16 v[48:51], v[182:185], v[190:193], v[48:51]
	v_mfma_f32_16x16x32_bf16 v[36:39], v[174:177], v[200:203], v[36:39]
	v_mfma_f32_16x16x32_bf16 v[32:35], v[182:185], v[200:203], v[32:35]
	v_mfma_f32_16x16x32_bf16 v[20:23], v[174:177], v[208:211], v[20:23]
	v_mfma_f32_16x16x32_bf16 v[16:19], v[182:185], v[208:211], v[16:19]
	v_mfma_f32_16x16x32_bf16 v[4:7], v[174:177], v[216:219], v[4:7]
	v_mfma_f32_16x16x32_bf16 v[0:3], v[182:185], v[216:219], v[0:3]
	v_mfma_f32_16x16x32_bf16 v[52:55], v[178:181], v[194:197], v[52:55]
	v_mfma_f32_16x16x32_bf16 v[48:51], v[186:189], v[194:197], v[48:51]
	v_mfma_f32_16x16x32_bf16 v[36:39], v[178:181], v[204:207], v[36:39]
	v_mfma_f32_16x16x32_bf16 v[32:35], v[186:189], v[204:207], v[32:35]
	v_mfma_f32_16x16x32_bf16 v[20:23], v[178:181], v[212:215], v[20:23]
	v_mfma_f32_16x16x32_bf16 v[16:19], v[186:189], v[212:215], v[16:19]
	v_mfma_f32_16x16x32_bf16 v[4:7], v[178:181], v[220:223], v[4:7]
	v_mfma_f32_16x16x32_bf16 v[0:3], v[186:189], v[220:223], v[0:3]
	s_setprio 0
	s_barrier
	s_add_i32 s67, 0, 0x18000
	s_add_i32 s70, 0, 0x1c000
	v_add_u32_e32 v170, s67, v157
	v_add_u32_e32 v186, s70, v157
	ds_read_b128 v[144:147], v170
	ds_read_b128 v[162:165], v170 offset:1024
	ds_read_b128 v[166:169], v170 offset:2048
	ds_read_b128 v[170:173], v170 offset:3072
	ds_read_b128 v[174:177], v186
	ds_read_b128 v[178:181], v186 offset:1024
	ds_read_b128 v[182:185], v186 offset:2048
	ds_read_b128 v[186:189], v186 offset:3072
	s_add_u32 s48, s48, 0x20000
	s_addc_u32 s49, s49, 0
	s_mov_b32 m0, s54
	v_lshl_add_u64 v[232:233], s[48:49], 0, v[128:129]
	ds_read_b128 v[190:193], v161 offset:32768
	ds_read_b128 v[194:197], v161 offset:33792
	ds_read_b128 v[200:203], v161 offset:34816
	ds_read_b128 v[204:207], v161 offset:35840
	ds_read_b128 v[208:211], v161 offset:36864
	ds_read_b128 v[212:215], v161 offset:37888
	ds_read_b128 v[216:219], v161 offset:38912
	ds_read_b128 v[220:223], v161 offset:39936
	global_load_lds_dwordx4 v[232:233], off
	v_lshl_add_u64 v[232:233], s[48:49], 0, v[132:133]
	s_mov_b32 m0, s55
	s_nop 0
	global_load_lds_dwordx4 v[232:233], off
	s_waitcnt vmcnt(8)
	s_waitcnt lgkmcnt(0)
	s_barrier
	s_setprio 1
	s_waitcnt lgkmcnt(0)
	v_mfma_f32_16x16x32_bf16 v[124:127], v[144:147], v[190:193], v[124:127]
	v_mfma_f32_16x16x32_bf16 v[120:123], v[166:169], v[190:193], v[120:123]
	v_mfma_f32_16x16x32_bf16 v[108:111], v[144:147], v[200:203], v[108:111]
	v_mfma_f32_16x16x32_bf16 v[104:107], v[166:169], v[200:203], v[104:107]
	v_mfma_f32_16x16x32_bf16 v[92:95], v[144:147], v[208:211], v[92:95]
	v_mfma_f32_16x16x32_bf16 v[88:91], v[166:169], v[208:211], v[88:91]
	v_mfma_f32_16x16x32_bf16 v[76:79], v[144:147], v[216:219], v[76:79]
	v_mfma_f32_16x16x32_bf16 v[72:75], v[166:169], v[216:219], v[72:75]
	v_mfma_f32_16x16x32_bf16 v[124:127], v[162:165], v[194:197], v[124:127]
	v_mfma_f32_16x16x32_bf16 v[120:123], v[170:173], v[194:197], v[120:123]
	v_mfma_f32_16x16x32_bf16 v[108:111], v[162:165], v[204:207], v[108:111]
	v_mfma_f32_16x16x32_bf16 v[104:107], v[170:173], v[204:207], v[104:107]
	v_mfma_f32_16x16x32_bf16 v[92:95], v[162:165], v[212:215], v[92:95]
	v_mfma_f32_16x16x32_bf16 v[88:91], v[170:173], v[212:215], v[88:91]
	v_mfma_f32_16x16x32_bf16 v[76:79], v[162:165], v[220:223], v[76:79]
	v_mfma_f32_16x16x32_bf16 v[72:75], v[170:173], v[220:223], v[72:75]
	v_mfma_f32_16x16x32_bf16 v[116:119], v[174:177], v[190:193], v[116:119]
	v_mfma_f32_16x16x32_bf16 v[112:115], v[182:185], v[190:193], v[112:115]
	v_mfma_f32_16x16x32_bf16 v[100:103], v[174:177], v[200:203], v[100:103]
	v_mfma_f32_16x16x32_bf16 v[96:99], v[182:185], v[200:203], v[96:99]
	v_mfma_f32_16x16x32_bf16 v[84:87], v[174:177], v[208:211], v[84:87]
	v_mfma_f32_16x16x32_bf16 v[80:83], v[182:185], v[208:211], v[80:83]
	v_mfma_f32_16x16x32_bf16 v[68:71], v[174:177], v[216:219], v[68:71]
	v_mfma_f32_16x16x32_bf16 v[64:67], v[182:185], v[216:219], v[64:67]
	v_mfma_f32_16x16x32_bf16 v[116:119], v[178:181], v[194:197], v[116:119]
	v_mfma_f32_16x16x32_bf16 v[112:115], v[186:189], v[194:197], v[112:115]
	v_mfma_f32_16x16x32_bf16 v[100:103], v[178:181], v[204:207], v[100:103]
	v_mfma_f32_16x16x32_bf16 v[96:99], v[186:189], v[204:207], v[96:99]
	v_mfma_f32_16x16x32_bf16 v[84:87], v[178:181], v[212:215], v[84:87]
	v_mfma_f32_16x16x32_bf16 v[80:83], v[186:189], v[212:215], v[80:83]
	v_mfma_f32_16x16x32_bf16 v[68:71], v[178:181], v[220:223], v[68:71]
	v_mfma_f32_16x16x32_bf16 v[64:67], v[186:189], v[220:223], v[64:67]
	s_setprio 0
	s_barrier
	s_add_i32 s48, s67, s52
	v_lshl_add_u64 v[224:225], v[224:225], 0, s[8:9]
	s_mov_b32 m0, s48
	ds_read_b128 v[190:193], v161 offset:49152
	ds_read_b128 v[194:197], v161 offset:50176
	ds_read_b128 v[200:203], v161 offset:51200
	ds_read_b128 v[204:207], v161 offset:52224
	ds_read_b128 v[208:211], v161 offset:53248
	ds_read_b128 v[212:215], v161 offset:54272
	ds_read_b128 v[216:219], v161 offset:55296
	ds_read_b128 v[220:223], v161 offset:56320
	global_load_lds_dwordx4 v[224:225], off
	s_add_i32 m0, s48, 0x2000
	s_add_u32 s46, s46, 0x20080
	v_lshl_add_u64 v[224:225], v[226:227], 0, s[8:9]
	s_addc_u32 s47, s47, 0
	s_add_i32 s48, s70, s52
	global_load_lds_dwordx4 v[224:225], off
	v_lshl_add_u64 v[224:225], s[46:47], 0, v[130:131]
	s_mov_b32 m0, s48
	s_nop 0
	global_load_lds_dwordx4 v[224:225], off
	v_lshl_add_u64 v[224:225], s[46:47], 0, v[134:135]
	s_add_i32 m0, s48, 0x2000
	s_nop 0
	global_load_lds_dwordx4 v[224:225], off
	v_lshl_add_u64 v[224:225], v[228:229], 0, s[8:9]
	s_mov_b32 m0, s57
	s_nop 0
	global_load_lds_dwordx4 v[224:225], off
	v_lshl_add_u64 v[224:225], v[230:231], 0, s[8:9]
	s_mov_b32 m0, s58
	s_nop 0
	global_load_lds_dwordx4 v[224:225], off
	s_waitcnt vmcnt(8)
	s_waitcnt lgkmcnt(0)
	s_barrier
	s_setprio 1
	s_waitcnt lgkmcnt(0)
	v_mfma_f32_16x16x32_bf16 v[60:63], v[144:147], v[190:193], v[60:63]
	v_mfma_f32_16x16x32_bf16 v[56:59], v[166:169], v[190:193], v[56:59]
	v_mfma_f32_16x16x32_bf16 v[44:47], v[144:147], v[200:203], v[44:47]
	v_mfma_f32_16x16x32_bf16 v[40:43], v[166:169], v[200:203], v[40:43]
	v_mfma_f32_16x16x32_bf16 v[28:31], v[144:147], v[208:211], v[28:31]
	v_mfma_f32_16x16x32_bf16 v[24:27], v[166:169], v[208:211], v[24:27]
	v_mfma_f32_16x16x32_bf16 v[12:15], v[144:147], v[216:219], v[12:15]
	v_mfma_f32_16x16x32_bf16 v[8:11], v[166:169], v[216:219], v[8:11]
	v_mfma_f32_16x16x32_bf16 v[60:63], v[162:165], v[194:197], v[60:63]
	v_mfma_f32_16x16x32_bf16 v[56:59], v[170:173], v[194:197], v[56:59]
	v_mfma_f32_16x16x32_bf16 v[44:47], v[162:165], v[204:207], v[44:47]
	v_mfma_f32_16x16x32_bf16 v[40:43], v[170:173], v[204:207], v[40:43]
	v_mfma_f32_16x16x32_bf16 v[28:31], v[162:165], v[212:215], v[28:31]
	v_mfma_f32_16x16x32_bf16 v[24:27], v[170:173], v[212:215], v[24:27]
	v_mfma_f32_16x16x32_bf16 v[12:15], v[162:165], v[220:223], v[12:15]
	v_mfma_f32_16x16x32_bf16 v[8:11], v[170:173], v[220:223], v[8:11]
	v_mfma_f32_16x16x32_bf16 v[52:55], v[174:177], v[190:193], v[52:55]
	v_mfma_f32_16x16x32_bf16 v[48:51], v[182:185], v[190:193], v[48:51]
	v_mfma_f32_16x16x32_bf16 v[36:39], v[174:177], v[200:203], v[36:39]
	v_mfma_f32_16x16x32_bf16 v[32:35], v[182:185], v[200:203], v[32:35]
	v_mfma_f32_16x16x32_bf16 v[20:23], v[174:177], v[208:211], v[20:23]
	v_mfma_f32_16x16x32_bf16 v[16:19], v[182:185], v[208:211], v[16:19]
	v_mfma_f32_16x16x32_bf16 v[4:7], v[174:177], v[216:219], v[4:7]
	v_mfma_f32_16x16x32_bf16 v[0:3], v[182:185], v[216:219], v[0:3]
	v_mfma_f32_16x16x32_bf16 v[52:55], v[178:181], v[194:197], v[52:55]
	v_mfma_f32_16x16x32_bf16 v[48:51], v[186:189], v[194:197], v[48:51]
	v_mfma_f32_16x16x32_bf16 v[36:39], v[178:181], v[204:207], v[36:39]
	v_mfma_f32_16x16x32_bf16 v[32:35], v[186:189], v[204:207], v[32:35]
	v_mfma_f32_16x16x32_bf16 v[20:23], v[178:181], v[212:215], v[20:23]
	v_mfma_f32_16x16x32_bf16 v[16:19], v[186:189], v[212:215], v[16:19]
	v_mfma_f32_16x16x32_bf16 v[4:7], v[178:181], v[220:223], v[4:7]
	v_mfma_f32_16x16x32_bf16 v[0:3], v[186:189], v[220:223], v[0:3]
	s_setprio 0
	s_barrier
	s_add_i32 s66, s66, 2
	s_add_u32 s44, s44, 0x100
	s_addc_u32 s45, s45, 0
	s_add_u32 s64, s64, 0x100
	s_addc_u32 s65, s65, 0
	s_cmp_gt_u32 s66, 5
	s_cbranch_scc0 .LBB0_1471
	s_and_b64 vcc, exec, s[12:13]
	s_cbranch_vccz .LBB0_1474
	s_barrier

.LBB0_1495:
	ds_read_b128 v[144:147], v153
	ds_read_b128 v[156:159], v153 offset:1024
	ds_read_b128 v[160:163], v153 offset:2048
	ds_read_b128 v[164:167], v153 offset:3072
	ds_read_b128 v[168:171], v154
	ds_read_b128 v[172:175], v154 offset:1024
	ds_read_b128 v[176:179], v154 offset:2048
	ds_read_b128 v[180:183], v154 offset:3072
	s_add_u32 s48, s46, 0xfffe0080
	s_addc_u32 s49, s47, -1
	s_cmp_eq_u32 s66, 4
	s_cselect_b32 s51, s10, s49
	s_cselect_b32 s50, s11, s48
	s_cselect_b32 s49, s21, s65
	s_cselect_b32 s48, s25, s64
	v_lshl_add_u64 v[148:149], s[46:47], 0, v[136:137]
	s_add_i32 m0, s45, 0xc000
	ds_read_b128 v[184:187], v155
	ds_read_b128 v[188:191], v155 offset:1024
	ds_read_b128 v[192:195], v155 offset:2048
	ds_read_b128 v[200:203], v155 offset:3072
	ds_read_b128 v[204:207], v155 offset:4096
	ds_read_b128 v[208:211], v155 offset:5120
	ds_read_b128 v[212:215], v155 offset:6144
	ds_read_b128 v[216:219], v155 offset:7168
	global_load_lds_dwordx4 v[148:149], off
	v_lshl_add_u64 v[148:149], s[46:47], 0, v[138:139]
	s_add_i32 m0, s45, 0xe000
	s_nop 0
	global_load_lds_dwordx4 v[148:149], off
	s_waitcnt vmcnt(8)
	s_waitcnt lgkmcnt(0)
	s_barrier
	s_setprio 1
	s_waitcnt lgkmcnt(0)
	v_mfma_f32_16x16x32_bf16 v[124:127], v[144:147], v[184:187], v[124:127]
	v_mfma_f32_16x16x32_bf16 v[120:123], v[160:163], v[184:187], v[120:123]
	v_mfma_f32_16x16x32_bf16 v[108:111], v[144:147], v[192:195], v[108:111]
	v_mfma_f32_16x16x32_bf16 v[104:107], v[160:163], v[192:195], v[104:107]
	v_mfma_f32_16x16x32_bf16 v[92:95], v[144:147], v[204:207], v[92:95]
	v_mfma_f32_16x16x32_bf16 v[88:91], v[160:163], v[204:207], v[88:91]
	v_mfma_f32_16x16x32_bf16 v[76:79], v[144:147], v[212:215], v[76:79]
	v_mfma_f32_16x16x32_bf16 v[72:75], v[160:163], v[212:215], v[72:75]
	v_mfma_f32_16x16x32_bf16 v[124:127], v[156:159], v[188:191], v[124:127]
	v_mfma_f32_16x16x32_bf16 v[120:123], v[164:167], v[188:191], v[120:123]
	v_mfma_f32_16x16x32_bf16 v[108:111], v[156:159], v[200:203], v[108:111]
	v_mfma_f32_16x16x32_bf16 v[104:107], v[164:167], v[200:203], v[104:107]
	v_mfma_f32_16x16x32_bf16 v[92:95], v[156:159], v[208:211], v[92:95]
	v_mfma_f32_16x16x32_bf16 v[88:91], v[164:167], v[208:211], v[88:91]
	v_mfma_f32_16x16x32_bf16 v[76:79], v[156:159], v[216:219], v[76:79]
	v_mfma_f32_16x16x32_bf16 v[72:75], v[164:167], v[216:219], v[72:75]
	v_mfma_f32_16x16x32_bf16 v[116:119], v[168:171], v[184:187], v[116:119]
	v_mfma_f32_16x16x32_bf16 v[112:115], v[176:179], v[184:187], v[112:115]
	v_mfma_f32_16x16x32_bf16 v[100:103], v[168:171], v[192:195], v[100:103]
	v_mfma_f32_16x16x32_bf16 v[96:99], v[176:179], v[192:195], v[96:99]
	v_mfma_f32_16x16x32_bf16 v[84:87], v[168:171], v[204:207], v[84:87]
	v_mfma_f32_16x16x32_bf16 v[80:83], v[176:179], v[204:207], v[80:83]
	v_mfma_f32_16x16x32_bf16 v[68:71], v[168:171], v[212:215], v[68:71]
	v_mfma_f32_16x16x32_bf16 v[64:67], v[176:179], v[212:215], v[64:67]
	v_mfma_f32_16x16x32_bf16 v[116:119], v[172:175], v[188:191], v[116:119]
	v_mfma_f32_16x16x32_bf16 v[112:115], v[180:183], v[188:191], v[112:115]
	v_mfma_f32_16x16x32_bf16 v[100:103], v[172:175], v[200:203], v[100:103]
	v_mfma_f32_16x16x32_bf16 v[96:99], v[180:183], v[200:203], v[96:99]
	v_mfma_f32_16x16x32_bf16 v[84:87], v[172:175], v[208:211], v[84:87]
	v_mfma_f32_16x16x32_bf16 v[80:83], v[180:183], v[208:211], v[80:83]
	v_mfma_f32_16x16x32_bf16 v[68:71], v[172:175], v[216:219], v[68:71]
	v_mfma_f32_16x16x32_bf16 v[64:67], v[180:183], v[216:219], v[64:67]
	s_setprio 0
	s_barrier
	s_add_i32 s67, s61, s52
	v_lshl_add_u64 v[148:149], s[48:49], 0, v[130:131]
	s_mov_b32 m0, s67
	ds_read_b128 v[184:187], v155 offset:16384
	ds_read_b128 v[188:191], v155 offset:17408
	ds_read_b128 v[192:195], v155 offset:18432
	ds_read_b128 v[200:203], v155 offset:19456
	ds_read_b128 v[204:207], v155 offset:20480
	ds_read_b128 v[208:211], v155 offset:21504
	ds_read_b128 v[212:215], v155 offset:22528
	ds_read_b128 v[216:219], v155 offset:23552
	global_load_lds_dwordx4 v[148:149], off
	s_add_i32 m0, s67, 0x2000
	s_add_u32 s70, s48, 0x20000
	v_lshl_add_u64 v[196:197], s[48:49], 0, v[134:135]
	s_addc_u32 s71, s49, 0
	s_add_i32 s67, s62, s52
	global_load_lds_dwordx4 v[196:197], off
	v_lshl_add_u64 v[220:221], s[70:71], 0, v[130:131]
	s_mov_b32 m0, s67
	v_lshl_add_u64 v[222:223], s[50:51], 0, v[132:133]
	global_load_lds_dwordx4 v[220:221], off
	v_lshl_add_u64 v[220:221], s[70:71], 0, v[134:135]
	s_add_i32 m0, s67, 0x2000
	s_nop 0
	global_load_lds_dwordx4 v[220:221], off
	v_lshl_add_u64 v[220:221], s[50:51], 0, v[128:129]
	s_mov_b32 m0, s45
	s_nop 0
	global_load_lds_dwordx4 v[220:221], off
	s_mov_b32 m0, s53
	s_nop 0
	global_load_lds_dwordx4 v[222:223], off
	s_waitcnt vmcnt(8)
	s_waitcnt lgkmcnt(0)
	s_barrier
	s_setprio 1
	s_waitcnt lgkmcnt(0)
	v_mfma_f32_16x16x32_bf16 v[60:63], v[144:147], v[184:187], v[60:63]
	v_mfma_f32_16x16x32_bf16 v[56:59], v[160:163], v[184:187], v[56:59]
	v_mfma_f32_16x16x32_bf16 v[44:47], v[144:147], v[192:195], v[44:47]
	v_mfma_f32_16x16x32_bf16 v[40:43], v[160:163], v[192:195], v[40:43]
	v_mfma_f32_16x16x32_bf16 v[28:31], v[144:147], v[204:207], v[28:31]
	v_mfma_f32_16x16x32_bf16 v[24:27], v[160:163], v[204:207], v[24:27]
	v_mfma_f32_16x16x32_bf16 v[12:15], v[144:147], v[212:215], v[12:15]
	v_mfma_f32_16x16x32_bf16 v[8:11], v[160:163], v[212:215], v[8:11]
	v_mfma_f32_16x16x32_bf16 v[60:63], v[156:159], v[188:191], v[60:63]
	v_mfma_f32_16x16x32_bf16 v[56:59], v[164:167], v[188:191], v[56:59]
	v_mfma_f32_16x16x32_bf16 v[44:47], v[156:159], v[200:203], v[44:47]
	v_mfma_f32_16x16x32_bf16 v[40:43], v[164:167], v[200:203], v[40:43]
	v_mfma_f32_16x16x32_bf16 v[28:31], v[156:159], v[208:211], v[28:31]
	v_mfma_f32_16x16x32_bf16 v[24:27], v[164:167], v[208:211], v[24:27]
	v_mfma_f32_16x16x32_bf16 v[12:15], v[156:159], v[216:219], v[12:15]
	v_mfma_f32_16x16x32_bf16 v[8:11], v[164:167], v[216:219], v[8:11]
	v_mfma_f32_16x16x32_bf16 v[52:55], v[168:171], v[184:187], v[52:55]
	v_mfma_f32_16x16x32_bf16 v[48:51], v[176:179], v[184:187], v[48:51]
	v_mfma_f32_16x16x32_bf16 v[36:39], v[168:171], v[192:195], v[36:39]
	v_mfma_f32_16x16x32_bf16 v[32:35], v[176:179], v[192:195], v[32:35]
	v_mfma_f32_16x16x32_bf16 v[20:23], v[168:171], v[204:207], v[20:23]
	v_mfma_f32_16x16x32_bf16 v[16:19], v[176:179], v[204:207], v[16:19]
	v_mfma_f32_16x16x32_bf16 v[4:7], v[168:171], v[212:215], v[4:7]
	v_mfma_f32_16x16x32_bf16 v[0:3], v[176:179], v[212:215], v[0:3]
	v_mfma_f32_16x16x32_bf16 v[52:55], v[172:175], v[188:191], v[52:55]
	v_mfma_f32_16x16x32_bf16 v[48:51], v[180:183], v[188:191], v[48:51]
	v_mfma_f32_16x16x32_bf16 v[36:39], v[172:175], v[200:203], v[36:39]
	v_mfma_f32_16x16x32_bf16 v[32:35], v[180:183], v[200:203], v[32:35]
	v_mfma_f32_16x16x32_bf16 v[20:23], v[172:175], v[208:211], v[20:23]
	v_mfma_f32_16x16x32_bf16 v[16:19], v[180:183], v[208:211], v[16:19]
	v_mfma_f32_16x16x32_bf16 v[4:7], v[172:175], v[216:219], v[4:7]
	v_mfma_f32_16x16x32_bf16 v[0:3], v[180:183], v[216:219], v[0:3]
	s_setprio 0
	s_barrier
	s_add_i32 s67, 0, 0x18000
	s_add_i32 s70, 0, 0x1c000
	v_add_u32_e32 v164, s67, v151
	v_add_u32_e32 v180, s70, v151
	ds_read_b128 v[144:147], v164
	ds_read_b128 v[156:159], v164 offset:1024
	ds_read_b128 v[160:163], v164 offset:2048
	ds_read_b128 v[164:167], v164 offset:3072
	ds_read_b128 v[168:171], v180
	ds_read_b128 v[172:175], v180 offset:1024
	ds_read_b128 v[176:179], v180 offset:2048
	ds_read_b128 v[180:183], v180 offset:3072
	s_add_u32 s50, s50, 0x20000
	s_addc_u32 s51, s51, 0
	s_mov_b32 m0, s54
	v_lshl_add_u64 v[224:225], s[50:51], 0, v[128:129]
	ds_read_b128 v[184:187], v155 offset:32768
	ds_read_b128 v[188:191], v155 offset:33792
	ds_read_b128 v[192:195], v155 offset:34816
	ds_read_b128 v[200:203], v155 offset:35840
	ds_read_b128 v[204:207], v155 offset:36864
	ds_read_b128 v[208:211], v155 offset:37888
	ds_read_b128 v[212:215], v155 offset:38912
	ds_read_b128 v[216:219], v155 offset:39936
	global_load_lds_dwordx4 v[224:225], off
	v_lshl_add_u64 v[224:225], s[50:51], 0, v[132:133]
	s_mov_b32 m0, s55
	s_nop 0
	global_load_lds_dwordx4 v[224:225], off
	s_waitcnt vmcnt(8)
	s_waitcnt lgkmcnt(0)
	s_barrier
	s_setprio 1
	s_waitcnt lgkmcnt(0)
	v_mfma_f32_16x16x32_bf16 v[124:127], v[144:147], v[184:187], v[124:127]
	v_mfma_f32_16x16x32_bf16 v[120:123], v[160:163], v[184:187], v[120:123]
	v_mfma_f32_16x16x32_bf16 v[108:111], v[144:147], v[192:195], v[108:111]
	v_mfma_f32_16x16x32_bf16 v[104:107], v[160:163], v[192:195], v[104:107]
	v_mfma_f32_16x16x32_bf16 v[92:95], v[144:147], v[204:207], v[92:95]
	v_mfma_f32_16x16x32_bf16 v[88:91], v[160:163], v[204:207], v[88:91]
	v_mfma_f32_16x16x32_bf16 v[76:79], v[144:147], v[212:215], v[76:79]
	v_mfma_f32_16x16x32_bf16 v[72:75], v[160:163], v[212:215], v[72:75]
	v_mfma_f32_16x16x32_bf16 v[124:127], v[156:159], v[188:191], v[124:127]
	v_mfma_f32_16x16x32_bf16 v[120:123], v[164:167], v[188:191], v[120:123]
	v_mfma_f32_16x16x32_bf16 v[108:111], v[156:159], v[200:203], v[108:111]
	v_mfma_f32_16x16x32_bf16 v[104:107], v[164:167], v[200:203], v[104:107]
	v_mfma_f32_16x16x32_bf16 v[92:95], v[156:159], v[208:211], v[92:95]
	v_mfma_f32_16x16x32_bf16 v[88:91], v[164:167], v[208:211], v[88:91]
	v_mfma_f32_16x16x32_bf16 v[76:79], v[156:159], v[216:219], v[76:79]
	v_mfma_f32_16x16x32_bf16 v[72:75], v[164:167], v[216:219], v[72:75]
	v_mfma_f32_16x16x32_bf16 v[116:119], v[168:171], v[184:187], v[116:119]
	v_mfma_f32_16x16x32_bf16 v[112:115], v[176:179], v[184:187], v[112:115]
	v_mfma_f32_16x16x32_bf16 v[100:103], v[168:171], v[192:195], v[100:103]
	v_mfma_f32_16x16x32_bf16 v[96:99], v[176:179], v[192:195], v[96:99]
	v_mfma_f32_16x16x32_bf16 v[84:87], v[168:171], v[204:207], v[84:87]
	v_mfma_f32_16x16x32_bf16 v[80:83], v[176:179], v[204:207], v[80:83]
	v_mfma_f32_16x16x32_bf16 v[68:71], v[168:171], v[212:215], v[68:71]
	v_mfma_f32_16x16x32_bf16 v[64:67], v[176:179], v[212:215], v[64:67]
	v_mfma_f32_16x16x32_bf16 v[116:119], v[172:175], v[188:191], v[116:119]
	v_mfma_f32_16x16x32_bf16 v[112:115], v[180:183], v[188:191], v[112:115]
	v_mfma_f32_16x16x32_bf16 v[100:103], v[172:175], v[200:203], v[100:103]
	v_mfma_f32_16x16x32_bf16 v[96:99], v[180:183], v[200:203], v[96:99]
	v_mfma_f32_16x16x32_bf16 v[84:87], v[172:175], v[208:211], v[84:87]
	v_mfma_f32_16x16x32_bf16 v[80:83], v[180:183], v[208:211], v[80:83]
	v_mfma_f32_16x16x32_bf16 v[68:71], v[172:175], v[216:219], v[68:71]
	v_mfma_f32_16x16x32_bf16 v[64:67], v[180:183], v[216:219], v[64:67]
	s_setprio 0
	s_barrier
	s_add_i32 s50, s67, s52
	v_lshl_add_u64 v[148:149], v[148:149], 0, s[6:7]
	s_mov_b32 m0, s50
	ds_read_b128 v[184:187], v155 offset:49152
	ds_read_b128 v[188:191], v155 offset:50176
	ds_read_b128 v[192:195], v155 offset:51200
	ds_read_b128 v[200:203], v155 offset:52224
	ds_read_b128 v[204:207], v155 offset:53248
	ds_read_b128 v[208:211], v155 offset:54272
	ds_read_b128 v[212:215], v155 offset:55296
	ds_read_b128 v[216:219], v155 offset:56320
	global_load_lds_dwordx4 v[148:149], off
	s_add_i32 m0, s50, 0x2000
	s_add_u32 s48, s48, 0x20080
	v_lshl_add_u64 v[148:149], v[196:197], 0, s[6:7]
	s_addc_u32 s49, s49, 0
	s_add_i32 s50, s70, s52
	global_load_lds_dwordx4 v[148:149], off
	v_lshl_add_u64 v[148:149], s[48:49], 0, v[130:131]
	s_mov_b32 m0, s50
	s_nop 0
	global_load_lds_dwordx4 v[148:149], off
	v_lshl_add_u64 v[148:149], s[48:49], 0, v[134:135]
	s_add_i32 m0, s50, 0x2000
	s_nop 0
	global_load_lds_dwordx4 v[148:149], off
	v_lshl_add_u64 v[148:149], v[220:221], 0, s[6:7]
	s_mov_b32 m0, s57
	s_nop 0
	global_load_lds_dwordx4 v[148:149], off
	v_lshl_add_u64 v[148:149], v[222:223], 0, s[6:7]
	s_mov_b32 m0, s58
	s_nop 0
	global_load_lds_dwordx4 v[148:149], off
	s_waitcnt vmcnt(8)
	s_waitcnt lgkmcnt(0)
	s_barrier
	s_setprio 1
	s_waitcnt lgkmcnt(0)
	v_mfma_f32_16x16x32_bf16 v[60:63], v[144:147], v[184:187], v[60:63]
	v_mfma_f32_16x16x32_bf16 v[56:59], v[160:163], v[184:187], v[56:59]
	v_mfma_f32_16x16x32_bf16 v[44:47], v[144:147], v[192:195], v[44:47]
	v_mfma_f32_16x16x32_bf16 v[40:43], v[160:163], v[192:195], v[40:43]
	v_mfma_f32_16x16x32_bf16 v[28:31], v[144:147], v[204:207], v[28:31]
	v_mfma_f32_16x16x32_bf16 v[24:27], v[160:163], v[204:207], v[24:27]
	v_mfma_f32_16x16x32_bf16 v[12:15], v[144:147], v[212:215], v[12:15]
	v_mfma_f32_16x16x32_bf16 v[8:11], v[160:163], v[212:215], v[8:11]
	v_mfma_f32_16x16x32_bf16 v[60:63], v[156:159], v[188:191], v[60:63]
	v_mfma_f32_16x16x32_bf16 v[56:59], v[164:167], v[188:191], v[56:59]
	v_mfma_f32_16x16x32_bf16 v[44:47], v[156:159], v[200:203], v[44:47]
	v_mfma_f32_16x16x32_bf16 v[40:43], v[164:167], v[200:203], v[40:43]
	v_mfma_f32_16x16x32_bf16 v[28:31], v[156:159], v[208:211], v[28:31]
	v_mfma_f32_16x16x32_bf16 v[24:27], v[164:167], v[208:211], v[24:27]
	v_mfma_f32_16x16x32_bf16 v[12:15], v[156:159], v[216:219], v[12:15]
	v_mfma_f32_16x16x32_bf16 v[8:11], v[164:167], v[216:219], v[8:11]
	v_mfma_f32_16x16x32_bf16 v[52:55], v[168:171], v[184:187], v[52:55]
	v_mfma_f32_16x16x32_bf16 v[48:51], v[176:179], v[184:187], v[48:51]
	v_mfma_f32_16x16x32_bf16 v[36:39], v[168:171], v[192:195], v[36:39]
	v_mfma_f32_16x16x32_bf16 v[32:35], v[176:179], v[192:195], v[32:35]
	v_mfma_f32_16x16x32_bf16 v[20:23], v[168:171], v[204:207], v[20:23]
	v_mfma_f32_16x16x32_bf16 v[16:19], v[176:179], v[204:207], v[16:19]
	v_mfma_f32_16x16x32_bf16 v[4:7], v[168:171], v[212:215], v[4:7]
	v_mfma_f32_16x16x32_bf16 v[0:3], v[176:179], v[212:215], v[0:3]
	v_mfma_f32_16x16x32_bf16 v[52:55], v[172:175], v[188:191], v[52:55]
	v_mfma_f32_16x16x32_bf16 v[48:51], v[180:183], v[188:191], v[48:51]
	v_mfma_f32_16x16x32_bf16 v[36:39], v[172:175], v[200:203], v[36:39]
	v_mfma_f32_16x16x32_bf16 v[32:35], v[180:183], v[200:203], v[32:35]
	v_mfma_f32_16x16x32_bf16 v[20:23], v[172:175], v[208:211], v[20:23]
	v_mfma_f32_16x16x32_bf16 v[16:19], v[180:183], v[208:211], v[16:19]
	v_mfma_f32_16x16x32_bf16 v[4:7], v[172:175], v[216:219], v[4:7]
	v_mfma_f32_16x16x32_bf16 v[0:3], v[180:183], v[216:219], v[0:3]
	s_setprio 0
	s_barrier
	s_add_i32 s66, s66, 2
	s_add_u32 s46, s46, 0x100
	s_addc_u32 s47, s47, 0
	s_add_u32 s64, s64, 0x100
	s_addc_u32 s65, s65, 0
	s_cmp_gt_u32 s66, 5
	s_cbranch_scc0 .LBB0_1495
	s_and_b64 vcc, exec, s[8:9]
	s_cbranch_vccz .LBB0_1498
	s_barrier

.LBB0_1576:
	ds_read_b128 v[88:91], v175
	ds_read_b128 v[92:95], v175 offset:1024
	ds_read_b128 v[96:99], v175 offset:2048
	ds_read_b128 v[100:103], v175 offset:3072
	ds_read_b128 v[160:163], v176
	ds_read_b128 v[164:167], v176 offset:1024
	ds_read_b128 v[168:171], v176 offset:2048
	ds_read_b128 v[180:183], v176 offset:3072
	s_add_u32 s50, s48, 0xfffc0080
	s_addc_u32 s51, s49, -1
	s_cmp_eq_u32 s76, 12
	s_cselect_b32 s53, s10, s51
	s_cselect_b32 s52, s11, s50
	s_cselect_b32 s51, s21, s75
	s_cselect_b32 s50, s25, s45
	v_lshl_add_u64 v[196:197], s[48:49], 0, v[152:153]
	s_add_i32 m0, s47, 0xc000
	ds_read_b128 v[184:187], v177
	ds_read_b128 v[188:191], v177 offset:1024
	ds_read_b128 v[192:195], v177 offset:2048
	ds_read_b128 v[200:203], v177 offset:3072
	ds_read_b128 v[204:207], v177 offset:4096
	ds_read_b128 v[208:211], v177 offset:5120
	ds_read_b128 v[212:215], v177 offset:6144
	ds_read_b128 v[216:219], v177 offset:7168
	global_load_lds_dwordx4 v[196:197], off
	v_lshl_add_u64 v[196:197], s[48:49], 0, v[154:155]
	s_add_i32 m0, s47, 0xe000
	s_nop 0
	global_load_lds_dwordx4 v[196:197], off
	s_waitcnt vmcnt(8)
	s_waitcnt lgkmcnt(0)
	s_barrier
	s_setprio 1
	s_waitcnt lgkmcnt(0)
	v_mfma_f32_16x16x32_bf16 v[140:143], v[88:91], v[184:187], v[140:143]
	v_mfma_f32_16x16x32_bf16 v[136:139], v[96:99], v[184:187], v[136:139]
	v_mfma_f32_16x16x32_bf16 v[124:127], v[88:91], v[192:195], v[124:127]
	v_mfma_f32_16x16x32_bf16 v[120:123], v[96:99], v[192:195], v[120:123]
	v_mfma_f32_16x16x32_bf16 v[108:111], v[88:91], v[204:207], v[108:111]
	v_mfma_f32_16x16x32_bf16 v[104:107], v[96:99], v[204:207], v[104:107]
	v_mfma_f32_16x16x32_bf16 v[76:79], v[88:91], v[212:215], v[76:79]
	v_mfma_f32_16x16x32_bf16 v[72:75], v[96:99], v[212:215], v[72:75]
	v_mfma_f32_16x16x32_bf16 v[140:143], v[92:95], v[188:191], v[140:143]
	v_mfma_f32_16x16x32_bf16 v[136:139], v[100:103], v[188:191], v[136:139]
	v_mfma_f32_16x16x32_bf16 v[124:127], v[92:95], v[200:203], v[124:127]
	v_mfma_f32_16x16x32_bf16 v[120:123], v[100:103], v[200:203], v[120:123]
	v_mfma_f32_16x16x32_bf16 v[108:111], v[92:95], v[208:211], v[108:111]
	v_mfma_f32_16x16x32_bf16 v[104:107], v[100:103], v[208:211], v[104:107]
	v_mfma_f32_16x16x32_bf16 v[76:79], v[92:95], v[216:219], v[76:79]
	v_mfma_f32_16x16x32_bf16 v[72:75], v[100:103], v[216:219], v[72:75]
	v_mfma_f32_16x16x32_bf16 v[132:135], v[160:163], v[184:187], v[132:135]
	v_mfma_f32_16x16x32_bf16 v[128:131], v[168:171], v[184:187], v[128:131]
	v_mfma_f32_16x16x32_bf16 v[116:119], v[160:163], v[192:195], v[116:119]
	v_mfma_f32_16x16x32_bf16 v[112:115], v[168:171], v[192:195], v[112:115]
	v_mfma_f32_16x16x32_bf16 v[84:87], v[160:163], v[204:207], v[84:87]
	v_mfma_f32_16x16x32_bf16 v[80:83], v[168:171], v[204:207], v[80:83]
	v_mfma_f32_16x16x32_bf16 v[68:71], v[160:163], v[212:215], v[68:71]
	v_mfma_f32_16x16x32_bf16 v[64:67], v[168:171], v[212:215], v[64:67]
	v_mfma_f32_16x16x32_bf16 v[132:135], v[164:167], v[188:191], v[132:135]
	v_mfma_f32_16x16x32_bf16 v[128:131], v[180:183], v[188:191], v[128:131]
	v_mfma_f32_16x16x32_bf16 v[116:119], v[164:167], v[200:203], v[116:119]
	v_mfma_f32_16x16x32_bf16 v[112:115], v[180:183], v[200:203], v[112:115]
	v_mfma_f32_16x16x32_bf16 v[84:87], v[164:167], v[208:211], v[84:87]
	v_mfma_f32_16x16x32_bf16 v[80:83], v[180:183], v[208:211], v[80:83]
	v_mfma_f32_16x16x32_bf16 v[68:71], v[164:167], v[216:219], v[68:71]
	v_mfma_f32_16x16x32_bf16 v[64:67], v[180:183], v[216:219], v[64:67]
	s_setprio 0
	s_barrier
	s_add_i32 s77, s67, s55
	v_lshl_add_u64 v[196:197], s[50:51], 0, v[146:147]
	s_mov_b32 m0, s77
	ds_read_b128 v[184:187], v177 offset:16384
	ds_read_b128 v[188:191], v177 offset:17408
	ds_read_b128 v[192:195], v177 offset:18432
	ds_read_b128 v[200:203], v177 offset:19456
	ds_read_b128 v[204:207], v177 offset:20480
	ds_read_b128 v[208:211], v177 offset:21504
	ds_read_b128 v[212:215], v177 offset:22528
	ds_read_b128 v[216:219], v177 offset:23552
	global_load_lds_dwordx4 v[196:197], off
	s_add_i32 m0, s77, 0x2000
	s_add_u32 s78, s50, 0x40000
	v_lshl_add_u64 v[220:221], s[50:51], 0, v[150:151]
	s_addc_u32 s79, s51, 0
	s_add_i32 s77, s70, s55
	global_load_lds_dwordx4 v[220:221], off
	v_lshl_add_u64 v[222:223], s[78:79], 0, v[146:147]
	s_mov_b32 m0, s77
	v_lshl_add_u64 v[224:225], s[52:53], 0, v[148:149]
	global_load_lds_dwordx4 v[222:223], off
	v_lshl_add_u64 v[222:223], s[78:79], 0, v[150:151]
	s_add_i32 m0, s77, 0x2000
	s_nop 0
	global_load_lds_dwordx4 v[222:223], off
	v_lshl_add_u64 v[222:223], s[52:53], 0, v[144:145]
	s_mov_b32 m0, s47
	s_nop 0
	global_load_lds_dwordx4 v[222:223], off
	s_mov_b32 m0, s56
	s_nop 0
	global_load_lds_dwordx4 v[224:225], off
	s_waitcnt vmcnt(8)
	s_waitcnt lgkmcnt(0)
	s_barrier
	s_setprio 1
	s_waitcnt lgkmcnt(0)
	v_mfma_f32_16x16x32_bf16 v[60:63], v[88:91], v[184:187], v[60:63]
	v_mfma_f32_16x16x32_bf16 v[56:59], v[96:99], v[184:187], v[56:59]
	v_mfma_f32_16x16x32_bf16 v[44:47], v[88:91], v[192:195], v[44:47]
	v_mfma_f32_16x16x32_bf16 v[40:43], v[96:99], v[192:195], v[40:43]
	v_mfma_f32_16x16x32_bf16 v[28:31], v[88:91], v[204:207], v[28:31]
	v_mfma_f32_16x16x32_bf16 v[24:27], v[96:99], v[204:207], v[24:27]
	v_mfma_f32_16x16x32_bf16 v[12:15], v[88:91], v[212:215], v[12:15]
	v_mfma_f32_16x16x32_bf16 v[8:11], v[96:99], v[212:215], v[8:11]
	v_mfma_f32_16x16x32_bf16 v[60:63], v[92:95], v[188:191], v[60:63]
	v_mfma_f32_16x16x32_bf16 v[56:59], v[100:103], v[188:191], v[56:59]
	v_mfma_f32_16x16x32_bf16 v[44:47], v[92:95], v[200:203], v[44:47]
	v_mfma_f32_16x16x32_bf16 v[40:43], v[100:103], v[200:203], v[40:43]
	v_mfma_f32_16x16x32_bf16 v[28:31], v[92:95], v[208:211], v[28:31]
	v_mfma_f32_16x16x32_bf16 v[24:27], v[100:103], v[208:211], v[24:27]
	v_mfma_f32_16x16x32_bf16 v[12:15], v[92:95], v[216:219], v[12:15]
	v_mfma_f32_16x16x32_bf16 v[8:11], v[100:103], v[216:219], v[8:11]
	v_mfma_f32_16x16x32_bf16 v[52:55], v[160:163], v[184:187], v[52:55]
	v_mfma_f32_16x16x32_bf16 v[48:51], v[168:171], v[184:187], v[48:51]
	v_mfma_f32_16x16x32_bf16 v[36:39], v[160:163], v[192:195], v[36:39]
	v_mfma_f32_16x16x32_bf16 v[32:35], v[168:171], v[192:195], v[32:35]
	v_mfma_f32_16x16x32_bf16 v[20:23], v[160:163], v[204:207], v[20:23]
	v_mfma_f32_16x16x32_bf16 v[16:19], v[168:171], v[204:207], v[16:19]
	v_mfma_f32_16x16x32_bf16 v[4:7], v[160:163], v[212:215], v[4:7]
	v_mfma_f32_16x16x32_bf16 v[0:3], v[168:171], v[212:215], v[0:3]
	v_mfma_f32_16x16x32_bf16 v[52:55], v[164:167], v[188:191], v[52:55]
	v_mfma_f32_16x16x32_bf16 v[48:51], v[180:183], v[188:191], v[48:51]
	v_mfma_f32_16x16x32_bf16 v[36:39], v[164:167], v[200:203], v[36:39]
	v_mfma_f32_16x16x32_bf16 v[32:35], v[180:183], v[200:203], v[32:35]
	v_mfma_f32_16x16x32_bf16 v[20:23], v[164:167], v[208:211], v[20:23]
	v_mfma_f32_16x16x32_bf16 v[16:19], v[180:183], v[208:211], v[16:19]
	v_mfma_f32_16x16x32_bf16 v[4:7], v[164:167], v[216:219], v[4:7]
	v_mfma_f32_16x16x32_bf16 v[0:3], v[180:183], v[216:219], v[0:3]
	s_setprio 0
	s_barrier
	s_add_i32 s77, 0, 0x18000
	s_add_i32 s78, 0, 0x1c000
	v_add_u32_e32 v100, s77, v173
	v_add_u32_e32 v179, s78, v173
	ds_read_b128 v[88:91], v100
	ds_read_b128 v[92:95], v100 offset:1024
	ds_read_b128 v[96:99], v100 offset:2048
	ds_read_b128 v[100:103], v100 offset:3072
	ds_read_b128 v[160:163], v179
	ds_read_b128 v[164:167], v179 offset:1024
	ds_read_b128 v[168:171], v179 offset:2048
	ds_read_b128 v[180:183], v179 offset:3072
	s_add_u32 s52, s52, 0x40000
	s_addc_u32 s53, s53, 0
	s_mov_b32 m0, s57
	v_lshl_add_u64 v[226:227], s[52:53], 0, v[144:145]
	ds_read_b128 v[184:187], v177 offset:32768
	ds_read_b128 v[188:191], v177 offset:33792
	ds_read_b128 v[192:195], v177 offset:34816
	ds_read_b128 v[200:203], v177 offset:35840
	ds_read_b128 v[204:207], v177 offset:36864
	ds_read_b128 v[208:211], v177 offset:37888
	ds_read_b128 v[212:215], v177 offset:38912
	ds_read_b128 v[216:219], v177 offset:39936
	global_load_lds_dwordx4 v[226:227], off
	v_lshl_add_u64 v[226:227], s[52:53], 0, v[148:149]
	s_mov_b32 m0, s58
	s_nop 0
	global_load_lds_dwordx4 v[226:227], off
	s_waitcnt vmcnt(8)
	s_waitcnt lgkmcnt(0)
	s_barrier
	s_setprio 1
	s_waitcnt lgkmcnt(0)
	v_mfma_f32_16x16x32_bf16 v[140:143], v[88:91], v[184:187], v[140:143]
	v_mfma_f32_16x16x32_bf16 v[136:139], v[96:99], v[184:187], v[136:139]
	v_mfma_f32_16x16x32_bf16 v[124:127], v[88:91], v[192:195], v[124:127]
	v_mfma_f32_16x16x32_bf16 v[120:123], v[96:99], v[192:195], v[120:123]
	v_mfma_f32_16x16x32_bf16 v[108:111], v[88:91], v[204:207], v[108:111]
	v_mfma_f32_16x16x32_bf16 v[104:107], v[96:99], v[204:207], v[104:107]
	v_mfma_f32_16x16x32_bf16 v[76:79], v[88:91], v[212:215], v[76:79]
	v_mfma_f32_16x16x32_bf16 v[72:75], v[96:99], v[212:215], v[72:75]
	v_mfma_f32_16x16x32_bf16 v[140:143], v[92:95], v[188:191], v[140:143]
	v_mfma_f32_16x16x32_bf16 v[136:139], v[100:103], v[188:191], v[136:139]
	v_mfma_f32_16x16x32_bf16 v[124:127], v[92:95], v[200:203], v[124:127]
	v_mfma_f32_16x16x32_bf16 v[120:123], v[100:103], v[200:203], v[120:123]
	v_mfma_f32_16x16x32_bf16 v[108:111], v[92:95], v[208:211], v[108:111]
	v_mfma_f32_16x16x32_bf16 v[104:107], v[100:103], v[208:211], v[104:107]
	v_mfma_f32_16x16x32_bf16 v[76:79], v[92:95], v[216:219], v[76:79]
	v_mfma_f32_16x16x32_bf16 v[72:75], v[100:103], v[216:219], v[72:75]
	v_mfma_f32_16x16x32_bf16 v[132:135], v[160:163], v[184:187], v[132:135]
	v_mfma_f32_16x16x32_bf16 v[128:131], v[168:171], v[184:187], v[128:131]
	v_mfma_f32_16x16x32_bf16 v[116:119], v[160:163], v[192:195], v[116:119]
	v_mfma_f32_16x16x32_bf16 v[112:115], v[168:171], v[192:195], v[112:115]
	v_mfma_f32_16x16x32_bf16 v[84:87], v[160:163], v[204:207], v[84:87]
	v_mfma_f32_16x16x32_bf16 v[80:83], v[168:171], v[204:207], v[80:83]
	v_mfma_f32_16x16x32_bf16 v[68:71], v[160:163], v[212:215], v[68:71]
	v_mfma_f32_16x16x32_bf16 v[64:67], v[168:171], v[212:215], v[64:67]
	v_mfma_f32_16x16x32_bf16 v[132:135], v[164:167], v[188:191], v[132:135]
	v_mfma_f32_16x16x32_bf16 v[128:131], v[180:183], v[188:191], v[128:131]
	v_mfma_f32_16x16x32_bf16 v[116:119], v[164:167], v[200:203], v[116:119]
	v_mfma_f32_16x16x32_bf16 v[112:115], v[180:183], v[200:203], v[112:115]
	v_mfma_f32_16x16x32_bf16 v[84:87], v[164:167], v[208:211], v[84:87]
	v_mfma_f32_16x16x32_bf16 v[80:83], v[180:183], v[208:211], v[80:83]
	v_mfma_f32_16x16x32_bf16 v[68:71], v[164:167], v[216:219], v[68:71]
	v_mfma_f32_16x16x32_bf16 v[64:67], v[180:183], v[216:219], v[64:67]
	s_setprio 0
	s_barrier
	s_add_i32 s52, s77, s55
	v_lshl_add_u64 v[196:197], v[196:197], 0, s[8:9]
	s_mov_b32 m0, s52
	ds_read_b128 v[184:187], v177 offset:49152
	ds_read_b128 v[188:191], v177 offset:50176
	ds_read_b128 v[192:195], v177 offset:51200
	ds_read_b128 v[200:203], v177 offset:52224
	ds_read_b128 v[204:207], v177 offset:53248
	ds_read_b128 v[208:211], v177 offset:54272
	ds_read_b128 v[212:215], v177 offset:55296
	ds_read_b128 v[216:219], v177 offset:56320
	global_load_lds_dwordx4 v[196:197], off
	s_add_i32 m0, s52, 0x2000
	s_add_u32 s50, s50, 0x40080
	v_lshl_add_u64 v[196:197], v[220:221], 0, s[8:9]
	s_addc_u32 s51, s51, 0
	s_add_i32 s52, s78, s55
	global_load_lds_dwordx4 v[196:197], off
	v_lshl_add_u64 v[196:197], s[50:51], 0, v[146:147]
	s_mov_b32 m0, s52
	s_nop 0
	global_load_lds_dwordx4 v[196:197], off
	v_lshl_add_u64 v[196:197], s[50:51], 0, v[150:151]
	s_add_i32 m0, s52, 0x2000
	s_nop 0
	global_load_lds_dwordx4 v[196:197], off
	v_lshl_add_u64 v[196:197], v[222:223], 0, s[8:9]
	s_mov_b32 m0, s61
	s_nop 0
	global_load_lds_dwordx4 v[196:197], off
	v_lshl_add_u64 v[196:197], v[224:225], 0, s[8:9]
	s_mov_b32 m0, s62
	s_nop 0
	global_load_lds_dwordx4 v[196:197], off
	s_waitcnt vmcnt(8)
	s_waitcnt lgkmcnt(0)
	s_barrier
	s_setprio 1
	s_waitcnt lgkmcnt(0)
	v_mfma_f32_16x16x32_bf16 v[60:63], v[88:91], v[184:187], v[60:63]
	v_mfma_f32_16x16x32_bf16 v[56:59], v[96:99], v[184:187], v[56:59]
	v_mfma_f32_16x16x32_bf16 v[44:47], v[88:91], v[192:195], v[44:47]
	v_mfma_f32_16x16x32_bf16 v[40:43], v[96:99], v[192:195], v[40:43]
	v_mfma_f32_16x16x32_bf16 v[28:31], v[88:91], v[204:207], v[28:31]
	v_mfma_f32_16x16x32_bf16 v[24:27], v[96:99], v[204:207], v[24:27]
	v_mfma_f32_16x16x32_bf16 v[12:15], v[88:91], v[212:215], v[12:15]
	v_mfma_f32_16x16x32_bf16 v[8:11], v[96:99], v[212:215], v[8:11]
	v_mfma_f32_16x16x32_bf16 v[60:63], v[92:95], v[188:191], v[60:63]
	v_mfma_f32_16x16x32_bf16 v[56:59], v[100:103], v[188:191], v[56:59]
	v_mfma_f32_16x16x32_bf16 v[44:47], v[92:95], v[200:203], v[44:47]
	v_mfma_f32_16x16x32_bf16 v[40:43], v[100:103], v[200:203], v[40:43]
	v_mfma_f32_16x16x32_bf16 v[28:31], v[92:95], v[208:211], v[28:31]
	v_mfma_f32_16x16x32_bf16 v[24:27], v[100:103], v[208:211], v[24:27]
	v_mfma_f32_16x16x32_bf16 v[12:15], v[92:95], v[216:219], v[12:15]
	v_mfma_f32_16x16x32_bf16 v[8:11], v[100:103], v[216:219], v[8:11]
	v_mfma_f32_16x16x32_bf16 v[52:55], v[160:163], v[184:187], v[52:55]
	v_mfma_f32_16x16x32_bf16 v[48:51], v[168:171], v[184:187], v[48:51]
	v_mfma_f32_16x16x32_bf16 v[36:39], v[160:163], v[192:195], v[36:39]
	v_mfma_f32_16x16x32_bf16 v[32:35], v[168:171], v[192:195], v[32:35]
	v_mfma_f32_16x16x32_bf16 v[20:23], v[160:163], v[204:207], v[20:23]
	v_mfma_f32_16x16x32_bf16 v[16:19], v[168:171], v[204:207], v[16:19]
	v_mfma_f32_16x16x32_bf16 v[4:7], v[160:163], v[212:215], v[4:7]
	v_mfma_f32_16x16x32_bf16 v[0:3], v[168:171], v[212:215], v[0:3]
	v_mfma_f32_16x16x32_bf16 v[52:55], v[164:167], v[188:191], v[52:55]
	v_mfma_f32_16x16x32_bf16 v[48:51], v[180:183], v[188:191], v[48:51]
	v_mfma_f32_16x16x32_bf16 v[36:39], v[164:167], v[200:203], v[36:39]
	v_mfma_f32_16x16x32_bf16 v[32:35], v[180:183], v[200:203], v[32:35]
	v_mfma_f32_16x16x32_bf16 v[20:23], v[164:167], v[208:211], v[20:23]
	v_mfma_f32_16x16x32_bf16 v[16:19], v[180:183], v[208:211], v[16:19]
	v_mfma_f32_16x16x32_bf16 v[4:7], v[164:167], v[216:219], v[4:7]
	v_mfma_f32_16x16x32_bf16 v[0:3], v[180:183], v[216:219], v[0:3]
	s_setprio 0
	s_barrier
	s_add_i32 s76, s76, 2
	s_add_u32 s48, s48, 0x100
	s_addc_u32 s49, s49, 0
	s_add_u32 s45, s45, 0x100
	s_addc_u32 s75, s75, 0
	s_cmp_gt_u32 s76, 13
	s_cbranch_scc0 .LBB0_1576
	s_and_b64 vcc, exec, s[12:13]
	s_cbranch_vccz .LBB0_1579
	s_barrier

.LBB0_1671:
	ds_read_b128 v[64:67], v176
	ds_read_b128 v[68:71], v176 offset:1024
	ds_read_b128 v[76:79], v176 offset:2048
	ds_read_b128 v[80:83], v176 offset:3072
	ds_read_b128 v[184:187], v177
	ds_read_b128 v[188:191], v177 offset:1024
	ds_read_b128 v[192:195], v177 offset:2048
	ds_read_b128 v[200:203], v177 offset:3072
	s_add_u32 s26, s24, 0xfffc0080
	s_addc_u32 s27, s25, -1
	s_cmp_eq_u32 s66, 12
	s_cselect_b32 s43, s1, s27
	s_cselect_b32 s42, s10, s26
	s_cselect_b32 s27, s11, s65
	s_cselect_b32 s26, s17, s19
	v_lshl_add_u64 v[162:163], s[24:25], 0, v[154:155]
	s_add_i32 m0, s49, 0xc000
	ds_read_b128 v[204:207], v178
	ds_read_b128 v[208:211], v178 offset:1024
	ds_read_b128 v[212:215], v178 offset:2048
	ds_read_b128 v[216:219], v178 offset:3072
	ds_read_b128 v[220:223], v178 offset:4096
	ds_read_b128 v[224:227], v178 offset:5120
	ds_read_b128 v[228:231], v178 offset:6144
	ds_read_b128 v[232:235], v178 offset:7168
	global_load_lds_dwordx4 v[162:163], off
	v_lshl_add_u64 v[162:163], s[24:25], 0, v[156:157]
	s_add_i32 m0, s49, 0xe000
	s_nop 0
	global_load_lds_dwordx4 v[162:163], off
	s_waitcnt vmcnt(8)
	s_waitcnt lgkmcnt(0)
	s_barrier
	s_setprio 1
	s_waitcnt lgkmcnt(0)
	v_mfma_f32_16x16x32_bf16 v[140:143], v[64:67], v[204:207], v[140:143]
	v_mfma_f32_16x16x32_bf16 v[132:135], v[76:79], v[204:207], v[132:135]
	v_mfma_f32_16x16x32_bf16 v[124:127], v[64:67], v[212:215], v[124:127]
	v_mfma_f32_16x16x32_bf16 v[120:123], v[76:79], v[212:215], v[120:123]
	v_mfma_f32_16x16x32_bf16 v[108:111], v[64:67], v[220:223], v[108:111]
	v_mfma_f32_16x16x32_bf16 v[104:107], v[76:79], v[220:223], v[104:107]
	v_mfma_f32_16x16x32_bf16 v[92:95], v[64:67], v[228:231], v[92:95]
	v_mfma_f32_16x16x32_bf16 v[88:91], v[76:79], v[228:231], v[88:91]
	v_mfma_f32_16x16x32_bf16 v[140:143], v[68:71], v[208:211], v[140:143]
	v_mfma_f32_16x16x32_bf16 v[132:135], v[80:83], v[208:211], v[132:135]
	v_mfma_f32_16x16x32_bf16 v[124:127], v[68:71], v[216:219], v[124:127]
	v_mfma_f32_16x16x32_bf16 v[120:123], v[80:83], v[216:219], v[120:123]
	v_mfma_f32_16x16x32_bf16 v[108:111], v[68:71], v[224:227], v[108:111]
	v_mfma_f32_16x16x32_bf16 v[104:107], v[80:83], v[224:227], v[104:107]
	v_mfma_f32_16x16x32_bf16 v[92:95], v[68:71], v[232:235], v[92:95]
	v_mfma_f32_16x16x32_bf16 v[88:91], v[80:83], v[232:235], v[88:91]
	v_mfma_f32_16x16x32_bf16 v[136:139], v[184:187], v[204:207], v[136:139]
	v_mfma_f32_16x16x32_bf16 v[128:131], v[192:195], v[204:207], v[128:131]
	v_mfma_f32_16x16x32_bf16 v[116:119], v[184:187], v[212:215], v[116:119]
	v_mfma_f32_16x16x32_bf16 v[112:115], v[192:195], v[212:215], v[112:115]
	v_mfma_f32_16x16x32_bf16 v[100:103], v[184:187], v[220:223], v[100:103]
	v_mfma_f32_16x16x32_bf16 v[96:99], v[192:195], v[220:223], v[96:99]
	v_mfma_f32_16x16x32_bf16 v[84:87], v[184:187], v[228:231], v[84:87]
	v_mfma_f32_16x16x32_bf16 v[72:75], v[192:195], v[228:231], v[72:75]
	v_mfma_f32_16x16x32_bf16 v[136:139], v[188:191], v[208:211], v[136:139]
	v_mfma_f32_16x16x32_bf16 v[128:131], v[200:203], v[208:211], v[128:131]
	v_mfma_f32_16x16x32_bf16 v[116:119], v[188:191], v[216:219], v[116:119]
	v_mfma_f32_16x16x32_bf16 v[112:115], v[200:203], v[216:219], v[112:115]
	v_mfma_f32_16x16x32_bf16 v[100:103], v[188:191], v[224:227], v[100:103]
	v_mfma_f32_16x16x32_bf16 v[96:99], v[200:203], v[224:227], v[96:99]
	v_mfma_f32_16x16x32_bf16 v[84:87], v[188:191], v[232:235], v[84:87]
	v_mfma_f32_16x16x32_bf16 v[72:75], v[200:203], v[232:235], v[72:75]
	s_setprio 0
	s_barrier
	s_add_i32 s67, s58, s48
	v_lshl_add_u64 v[162:163], s[26:27], 0, v[146:147]
	s_mov_b32 m0, s67
	ds_read_b128 v[204:207], v178 offset:16384
	ds_read_b128 v[208:211], v178 offset:17408
	ds_read_b128 v[212:215], v178 offset:18432
	ds_read_b128 v[216:219], v178 offset:19456
	ds_read_b128 v[220:223], v178 offset:20480
	ds_read_b128 v[224:227], v178 offset:21504
	ds_read_b128 v[228:231], v178 offset:22528
	ds_read_b128 v[232:235], v178 offset:23552
	global_load_lds_dwordx4 v[162:163], off
	s_add_i32 m0, s67, 0x2000
	s_add_u32 s70, s26, 0x40000
	v_lshl_add_u64 v[196:197], s[26:27], 0, v[150:151]
	s_addc_u32 s71, s27, 0
	s_add_i32 s67, s59, s48
	global_load_lds_dwordx4 v[196:197], off
	v_lshl_add_u64 v[236:237], s[70:71], 0, v[146:147]
	s_mov_b32 m0, s67
	v_lshl_add_u64 v[238:239], s[42:43], 0, v[148:149]
	global_load_lds_dwordx4 v[236:237], off
	v_lshl_add_u64 v[236:237], s[70:71], 0, v[150:151]
	s_add_i32 m0, s67, 0x2000
	s_nop 0
	global_load_lds_dwordx4 v[236:237], off
	v_lshl_add_u64 v[236:237], s[42:43], 0, v[144:145]
	s_mov_b32 m0, s49
	s_nop 0
	global_load_lds_dwordx4 v[236:237], off
	s_mov_b32 m0, s50
	s_nop 0
	global_load_lds_dwordx4 v[238:239], off
	s_waitcnt vmcnt(8)
	s_waitcnt lgkmcnt(0)
	s_barrier
	s_setprio 1
	s_waitcnt lgkmcnt(0)
	v_mfma_f32_16x16x32_bf16 v[60:63], v[64:67], v[204:207], v[60:63]
	v_mfma_f32_16x16x32_bf16 v[56:59], v[76:79], v[204:207], v[56:59]
	v_mfma_f32_16x16x32_bf16 v[44:47], v[64:67], v[212:215], v[44:47]
	v_mfma_f32_16x16x32_bf16 v[40:43], v[76:79], v[212:215], v[40:43]
	v_mfma_f32_16x16x32_bf16 v[28:31], v[64:67], v[220:223], v[28:31]
	v_mfma_f32_16x16x32_bf16 v[24:27], v[76:79], v[220:223], v[24:27]
	v_mfma_f32_16x16x32_bf16 v[12:15], v[64:67], v[228:231], v[12:15]
	v_mfma_f32_16x16x32_bf16 v[8:11], v[76:79], v[228:231], v[8:11]
	v_mfma_f32_16x16x32_bf16 v[60:63], v[68:71], v[208:211], v[60:63]
	v_mfma_f32_16x16x32_bf16 v[56:59], v[80:83], v[208:211], v[56:59]
	v_mfma_f32_16x16x32_bf16 v[44:47], v[68:71], v[216:219], v[44:47]
	v_mfma_f32_16x16x32_bf16 v[40:43], v[80:83], v[216:219], v[40:43]
	v_mfma_f32_16x16x32_bf16 v[28:31], v[68:71], v[224:227], v[28:31]
	v_mfma_f32_16x16x32_bf16 v[24:27], v[80:83], v[224:227], v[24:27]
	v_mfma_f32_16x16x32_bf16 v[12:15], v[68:71], v[232:235], v[12:15]
	v_mfma_f32_16x16x32_bf16 v[8:11], v[80:83], v[232:235], v[8:11]
	v_mfma_f32_16x16x32_bf16 v[52:55], v[184:187], v[204:207], v[52:55]
	v_mfma_f32_16x16x32_bf16 v[48:51], v[192:195], v[204:207], v[48:51]
	v_mfma_f32_16x16x32_bf16 v[36:39], v[184:187], v[212:215], v[36:39]
	v_mfma_f32_16x16x32_bf16 v[32:35], v[192:195], v[212:215], v[32:35]
	v_mfma_f32_16x16x32_bf16 v[20:23], v[184:187], v[220:223], v[20:23]
	v_mfma_f32_16x16x32_bf16 v[16:19], v[192:195], v[220:223], v[16:19]
	v_mfma_f32_16x16x32_bf16 v[4:7], v[184:187], v[228:231], v[4:7]
	v_mfma_f32_16x16x32_bf16 v[0:3], v[192:195], v[228:231], v[0:3]
	v_mfma_f32_16x16x32_bf16 v[52:55], v[188:191], v[208:211], v[52:55]
	v_mfma_f32_16x16x32_bf16 v[48:51], v[200:203], v[208:211], v[48:51]
	v_mfma_f32_16x16x32_bf16 v[36:39], v[188:191], v[216:219], v[36:39]
	v_mfma_f32_16x16x32_bf16 v[32:35], v[200:203], v[216:219], v[32:35]
	v_mfma_f32_16x16x32_bf16 v[20:23], v[188:191], v[224:227], v[20:23]
	v_mfma_f32_16x16x32_bf16 v[16:19], v[200:203], v[224:227], v[16:19]
	v_mfma_f32_16x16x32_bf16 v[4:7], v[188:191], v[232:235], v[4:7]
	v_mfma_f32_16x16x32_bf16 v[0:3], v[200:203], v[232:235], v[0:3]
	s_setprio 0
	s_barrier
	s_add_i32 s67, 0, 0x18000
	s_add_i32 s70, 0, 0x1c000
	v_add_u32_e32 v80, s67, v166
	v_add_u32_e32 v164, s70, v166
	ds_read_b128 v[64:67], v80
	ds_read_b128 v[68:71], v80 offset:1024
	ds_read_b128 v[76:79], v80 offset:2048
	ds_read_b128 v[80:83], v80 offset:3072
	ds_read_b128 v[184:187], v164
	ds_read_b128 v[188:191], v164 offset:1024
	ds_read_b128 v[192:195], v164 offset:2048
	ds_read_b128 v[200:203], v164 offset:3072
	s_add_u32 s42, s42, 0x40000
	s_addc_u32 s43, s43, 0
	s_mov_b32 m0, s51
	v_lshl_add_u64 v[240:241], s[42:43], 0, v[144:145]
	ds_read_b128 v[204:207], v178 offset:32768
	ds_read_b128 v[208:211], v178 offset:33792
	ds_read_b128 v[212:215], v178 offset:34816
	ds_read_b128 v[216:219], v178 offset:35840
	ds_read_b128 v[220:223], v178 offset:36864
	ds_read_b128 v[224:227], v178 offset:37888
	ds_read_b128 v[228:231], v178 offset:38912
	ds_read_b128 v[232:235], v178 offset:39936
	global_load_lds_dwordx4 v[240:241], off
	v_lshl_add_u64 v[240:241], s[42:43], 0, v[148:149]
	s_mov_b32 m0, s52
	s_nop 0
	global_load_lds_dwordx4 v[240:241], off
	s_waitcnt vmcnt(8)
	s_waitcnt lgkmcnt(0)
	s_barrier
	s_setprio 1
	s_waitcnt lgkmcnt(0)
	v_mfma_f32_16x16x32_bf16 v[140:143], v[64:67], v[204:207], v[140:143]
	v_mfma_f32_16x16x32_bf16 v[132:135], v[76:79], v[204:207], v[132:135]
	v_mfma_f32_16x16x32_bf16 v[124:127], v[64:67], v[212:215], v[124:127]
	v_mfma_f32_16x16x32_bf16 v[120:123], v[76:79], v[212:215], v[120:123]
	v_mfma_f32_16x16x32_bf16 v[108:111], v[64:67], v[220:223], v[108:111]
	v_mfma_f32_16x16x32_bf16 v[104:107], v[76:79], v[220:223], v[104:107]
	v_mfma_f32_16x16x32_bf16 v[92:95], v[64:67], v[228:231], v[92:95]
	v_mfma_f32_16x16x32_bf16 v[88:91], v[76:79], v[228:231], v[88:91]
	v_mfma_f32_16x16x32_bf16 v[140:143], v[68:71], v[208:211], v[140:143]
	v_mfma_f32_16x16x32_bf16 v[132:135], v[80:83], v[208:211], v[132:135]
	v_mfma_f32_16x16x32_bf16 v[124:127], v[68:71], v[216:219], v[124:127]
	v_mfma_f32_16x16x32_bf16 v[120:123], v[80:83], v[216:219], v[120:123]
	v_mfma_f32_16x16x32_bf16 v[108:111], v[68:71], v[224:227], v[108:111]
	v_mfma_f32_16x16x32_bf16 v[104:107], v[80:83], v[224:227], v[104:107]
	v_mfma_f32_16x16x32_bf16 v[92:95], v[68:71], v[232:235], v[92:95]
	v_mfma_f32_16x16x32_bf16 v[88:91], v[80:83], v[232:235], v[88:91]
	v_mfma_f32_16x16x32_bf16 v[136:139], v[184:187], v[204:207], v[136:139]
	v_mfma_f32_16x16x32_bf16 v[128:131], v[192:195], v[204:207], v[128:131]
	v_mfma_f32_16x16x32_bf16 v[116:119], v[184:187], v[212:215], v[116:119]
	v_mfma_f32_16x16x32_bf16 v[112:115], v[192:195], v[212:215], v[112:115]
	v_mfma_f32_16x16x32_bf16 v[100:103], v[184:187], v[220:223], v[100:103]
	v_mfma_f32_16x16x32_bf16 v[96:99], v[192:195], v[220:223], v[96:99]
	v_mfma_f32_16x16x32_bf16 v[84:87], v[184:187], v[228:231], v[84:87]
	v_mfma_f32_16x16x32_bf16 v[72:75], v[192:195], v[228:231], v[72:75]
	v_mfma_f32_16x16x32_bf16 v[136:139], v[188:191], v[208:211], v[136:139]
	v_mfma_f32_16x16x32_bf16 v[128:131], v[200:203], v[208:211], v[128:131]
	v_mfma_f32_16x16x32_bf16 v[116:119], v[188:191], v[216:219], v[116:119]
	v_mfma_f32_16x16x32_bf16 v[112:115], v[200:203], v[216:219], v[112:115]
	v_mfma_f32_16x16x32_bf16 v[100:103], v[188:191], v[224:227], v[100:103]
	v_mfma_f32_16x16x32_bf16 v[96:99], v[200:203], v[224:227], v[96:99]
	v_mfma_f32_16x16x32_bf16 v[84:87], v[188:191], v[232:235], v[84:87]
	v_mfma_f32_16x16x32_bf16 v[72:75], v[200:203], v[232:235], v[72:75]
	s_setprio 0
	s_barrier
	s_add_i32 s42, s67, s48
	v_lshl_add_u64 v[162:163], v[162:163], 0, s[12:13]
	s_mov_b32 m0, s42
	ds_read_b128 v[204:207], v178 offset:49152
	ds_read_b128 v[208:211], v178 offset:50176
	ds_read_b128 v[212:215], v178 offset:51200
	ds_read_b128 v[216:219], v178 offset:52224
	ds_read_b128 v[220:223], v178 offset:53248
	ds_read_b128 v[224:227], v178 offset:54272
	ds_read_b128 v[228:231], v178 offset:55296
	ds_read_b128 v[232:235], v178 offset:56320
	global_load_lds_dwordx4 v[162:163], off
	s_add_i32 m0, s42, 0x2000
	s_add_u32 s26, s26, 0x40080
	v_lshl_add_u64 v[162:163], v[196:197], 0, s[12:13]
	s_addc_u32 s27, s27, 0
	s_add_i32 s42, s70, s48
	global_load_lds_dwordx4 v[162:163], off
	v_lshl_add_u64 v[162:163], s[26:27], 0, v[146:147]
	s_mov_b32 m0, s42
	s_nop 0
	global_load_lds_dwordx4 v[162:163], off
	v_lshl_add_u64 v[162:163], s[26:27], 0, v[150:151]
	s_add_i32 m0, s42, 0x2000
	s_nop 0
	global_load_lds_dwordx4 v[162:163], off
	v_lshl_add_u64 v[162:163], v[236:237], 0, s[12:13]
	s_mov_b32 m0, s55
	s_nop 0
	global_load_lds_dwordx4 v[162:163], off
	v_lshl_add_u64 v[162:163], v[238:239], 0, s[12:13]
	s_mov_b32 m0, s56
	s_nop 0
	global_load_lds_dwordx4 v[162:163], off
	s_waitcnt vmcnt(8)
	s_waitcnt lgkmcnt(0)
	s_barrier
	s_setprio 1
	s_waitcnt lgkmcnt(0)
	v_mfma_f32_16x16x32_bf16 v[60:63], v[64:67], v[204:207], v[60:63]
	v_mfma_f32_16x16x32_bf16 v[56:59], v[76:79], v[204:207], v[56:59]
	v_mfma_f32_16x16x32_bf16 v[44:47], v[64:67], v[212:215], v[44:47]
	v_mfma_f32_16x16x32_bf16 v[40:43], v[76:79], v[212:215], v[40:43]
	v_mfma_f32_16x16x32_bf16 v[28:31], v[64:67], v[220:223], v[28:31]
	v_mfma_f32_16x16x32_bf16 v[24:27], v[76:79], v[220:223], v[24:27]
	v_mfma_f32_16x16x32_bf16 v[12:15], v[64:67], v[228:231], v[12:15]
	v_mfma_f32_16x16x32_bf16 v[8:11], v[76:79], v[228:231], v[8:11]
	v_mfma_f32_16x16x32_bf16 v[60:63], v[68:71], v[208:211], v[60:63]
	v_mfma_f32_16x16x32_bf16 v[56:59], v[80:83], v[208:211], v[56:59]
	v_mfma_f32_16x16x32_bf16 v[44:47], v[68:71], v[216:219], v[44:47]
	v_mfma_f32_16x16x32_bf16 v[40:43], v[80:83], v[216:219], v[40:43]
	v_mfma_f32_16x16x32_bf16 v[28:31], v[68:71], v[224:227], v[28:31]
	v_mfma_f32_16x16x32_bf16 v[24:27], v[80:83], v[224:227], v[24:27]
	v_mfma_f32_16x16x32_bf16 v[12:15], v[68:71], v[232:235], v[12:15]
	v_mfma_f32_16x16x32_bf16 v[8:11], v[80:83], v[232:235], v[8:11]
	v_mfma_f32_16x16x32_bf16 v[52:55], v[184:187], v[204:207], v[52:55]
	v_mfma_f32_16x16x32_bf16 v[48:51], v[192:195], v[204:207], v[48:51]
	v_mfma_f32_16x16x32_bf16 v[36:39], v[184:187], v[212:215], v[36:39]
	v_mfma_f32_16x16x32_bf16 v[32:35], v[192:195], v[212:215], v[32:35]
	v_mfma_f32_16x16x32_bf16 v[20:23], v[184:187], v[220:223], v[20:23]
	v_mfma_f32_16x16x32_bf16 v[16:19], v[192:195], v[220:223], v[16:19]
	v_mfma_f32_16x16x32_bf16 v[4:7], v[184:187], v[228:231], v[4:7]
	v_mfma_f32_16x16x32_bf16 v[0:3], v[192:195], v[228:231], v[0:3]
	v_mfma_f32_16x16x32_bf16 v[52:55], v[188:191], v[208:211], v[52:55]
	v_mfma_f32_16x16x32_bf16 v[48:51], v[200:203], v[208:211], v[48:51]
	v_mfma_f32_16x16x32_bf16 v[36:39], v[188:191], v[216:219], v[36:39]
	v_mfma_f32_16x16x32_bf16 v[32:35], v[200:203], v[216:219], v[32:35]
	v_mfma_f32_16x16x32_bf16 v[20:23], v[188:191], v[224:227], v[20:23]
	v_mfma_f32_16x16x32_bf16 v[16:19], v[200:203], v[224:227], v[16:19]
	v_mfma_f32_16x16x32_bf16 v[4:7], v[188:191], v[232:235], v[4:7]
	v_mfma_f32_16x16x32_bf16 v[0:3], v[200:203], v[232:235], v[0:3]
	s_setprio 0
	s_barrier
	s_add_i32 s66, s66, 2
	s_add_u32 s24, s24, 0x100
	s_addc_u32 s25, s25, 0
	s_add_u32 s19, s19, 0x100
	s_addc_u32 s65, s65, 0
	s_cmp_gt_u32 s66, 13
	s_cbranch_scc0 .LBB0_1671
	s_and_b64 vcc, exec, s[14:15]
	s_cbranch_vccz .LBB0_1674
	s_barrier

.LBB0_1786:
	ds_read_b128 v[144:147], v167
	ds_read_b128 v[148:151], v167 offset:1024
	ds_read_b128 v[152:155], v167 offset:2048
	ds_read_b128 v[156:159], v167 offset:3072
	ds_read_b128 v[160:163], v168
	ds_read_b128 v[170:173], v168 offset:1024
	ds_read_b128 v[174:177], v168 offset:2048
	ds_read_b128 v[178:181], v168 offset:3072
	s_add_u32 s16, s14, 0xfff50080
	s_addc_u32 s17, s15, -1
	s_cmp_eq_u32 s50, 40
	s_cselect_b32 s19, s3, s17
	s_cselect_b32 s18, s2, s16
	s_cselect_b32 s17, s13, s49
	s_cselect_b32 s16, s12, s48
	v_lshl_add_u64 v[214:215], s[14:15], 0, v[136:137]
	s_add_i32 m0, s24, 0xc000
	ds_read_b128 v[182:185], v169
	ds_read_b128 v[186:189], v169 offset:1024
	ds_read_b128 v[190:193], v169 offset:2048
	ds_read_b128 v[194:197], v169 offset:3072
	ds_read_b128 v[198:201], v169 offset:4096
	ds_read_b128 v[202:205], v169 offset:5120
	ds_read_b128 v[206:209], v169 offset:6144
	ds_read_b128 v[210:213], v169 offset:7168
	global_load_lds_dwordx4 v[214:215], off
	v_lshl_add_u64 v[214:215], s[14:15], 0, v[138:139]
	s_add_i32 m0, s24, 0xe000
	s_nop 0
	global_load_lds_dwordx4 v[214:215], off
	s_waitcnt vmcnt(8)
	s_waitcnt lgkmcnt(0)
	s_barrier
	s_setprio 1
	s_waitcnt lgkmcnt(0)
	v_mfma_f32_16x16x32_bf16 v[124:127], v[144:147], v[182:185], v[124:127]
	v_mfma_f32_16x16x32_bf16 v[120:123], v[152:155], v[182:185], v[120:123]
	v_mfma_f32_16x16x32_bf16 v[108:111], v[144:147], v[190:193], v[108:111]
	v_mfma_f32_16x16x32_bf16 v[104:107], v[152:155], v[190:193], v[104:107]
	v_mfma_f32_16x16x32_bf16 v[92:95], v[144:147], v[198:201], v[92:95]
	v_mfma_f32_16x16x32_bf16 v[88:91], v[152:155], v[198:201], v[88:91]
	v_mfma_f32_16x16x32_bf16 v[76:79], v[144:147], v[206:209], v[76:79]
	v_mfma_f32_16x16x32_bf16 v[72:75], v[152:155], v[206:209], v[72:75]
	v_mfma_f32_16x16x32_bf16 v[124:127], v[148:151], v[186:189], v[124:127]
	v_mfma_f32_16x16x32_bf16 v[120:123], v[156:159], v[186:189], v[120:123]
	v_mfma_f32_16x16x32_bf16 v[108:111], v[148:151], v[194:197], v[108:111]
	v_mfma_f32_16x16x32_bf16 v[104:107], v[156:159], v[194:197], v[104:107]
	v_mfma_f32_16x16x32_bf16 v[92:95], v[148:151], v[202:205], v[92:95]
	v_mfma_f32_16x16x32_bf16 v[88:91], v[156:159], v[202:205], v[88:91]
	v_mfma_f32_16x16x32_bf16 v[76:79], v[148:151], v[210:213], v[76:79]
	v_mfma_f32_16x16x32_bf16 v[72:75], v[156:159], v[210:213], v[72:75]
	v_mfma_f32_16x16x32_bf16 v[116:119], v[160:163], v[182:185], v[116:119]
	v_mfma_f32_16x16x32_bf16 v[112:115], v[174:177], v[182:185], v[112:115]
	v_mfma_f32_16x16x32_bf16 v[100:103], v[160:163], v[190:193], v[100:103]
	v_mfma_f32_16x16x32_bf16 v[96:99], v[174:177], v[190:193], v[96:99]
	v_mfma_f32_16x16x32_bf16 v[84:87], v[160:163], v[198:201], v[84:87]
	v_mfma_f32_16x16x32_bf16 v[80:83], v[174:177], v[198:201], v[80:83]
	v_mfma_f32_16x16x32_bf16 v[68:71], v[160:163], v[206:209], v[68:71]
	v_mfma_f32_16x16x32_bf16 v[64:67], v[174:177], v[206:209], v[64:67]
	v_mfma_f32_16x16x32_bf16 v[116:119], v[170:173], v[186:189], v[116:119]
	v_mfma_f32_16x16x32_bf16 v[112:115], v[178:181], v[186:189], v[112:115]
	v_mfma_f32_16x16x32_bf16 v[100:103], v[170:173], v[194:197], v[100:103]
	v_mfma_f32_16x16x32_bf16 v[96:99], v[178:181], v[194:197], v[96:99]
	v_mfma_f32_16x16x32_bf16 v[84:87], v[170:173], v[202:205], v[84:87]
	v_mfma_f32_16x16x32_bf16 v[80:83], v[178:181], v[202:205], v[80:83]
	v_mfma_f32_16x16x32_bf16 v[68:71], v[170:173], v[210:213], v[68:71]
	v_mfma_f32_16x16x32_bf16 v[64:67], v[178:181], v[210:213], v[64:67]
	s_setprio 0
	s_barrier
	s_add_i32 s51, s41, s23
	v_lshl_add_u64 v[214:215], s[16:17], 0, v[130:131]
	s_mov_b32 m0, s51
	ds_read_b128 v[182:185], v169 offset:16384
	ds_read_b128 v[186:189], v169 offset:17408
	ds_read_b128 v[190:193], v169 offset:18432
	ds_read_b128 v[194:197], v169 offset:19456
	ds_read_b128 v[198:201], v169 offset:20480
	ds_read_b128 v[202:205], v169 offset:21504
	ds_read_b128 v[206:209], v169 offset:22528
	ds_read_b128 v[210:213], v169 offset:23552
	global_load_lds_dwordx4 v[214:215], off
	s_add_i32 m0, s51, 0x2000
	s_add_u32 s52, s16, 0xb0000
	v_lshl_add_u64 v[216:217], s[16:17], 0, v[134:135]
	s_addc_u32 s53, s17, 0
	s_add_i32 s51, s42, s23
	global_load_lds_dwordx4 v[216:217], off
	v_lshl_add_u64 v[218:219], s[52:53], 0, v[130:131]
	s_mov_b32 m0, s51
	v_lshl_add_u64 v[220:221], s[18:19], 0, v[132:133]
	global_load_lds_dwordx4 v[218:219], off
	v_lshl_add_u64 v[218:219], s[52:53], 0, v[134:135]
	s_add_i32 m0, s51, 0x2000
	s_nop 0
	global_load_lds_dwordx4 v[218:219], off
	v_lshl_add_u64 v[218:219], s[18:19], 0, v[128:129]
	s_mov_b32 m0, s24
	s_nop 0
	global_load_lds_dwordx4 v[218:219], off
	s_mov_b32 m0, s25
	s_nop 0
	global_load_lds_dwordx4 v[220:221], off
	s_waitcnt vmcnt(8)
	s_waitcnt lgkmcnt(0)
	s_barrier
	s_setprio 1
	s_waitcnt lgkmcnt(0)
	v_mfma_f32_16x16x32_bf16 v[60:63], v[144:147], v[182:185], v[60:63]
	v_mfma_f32_16x16x32_bf16 v[56:59], v[152:155], v[182:185], v[56:59]
	v_mfma_f32_16x16x32_bf16 v[44:47], v[144:147], v[190:193], v[44:47]
	v_mfma_f32_16x16x32_bf16 v[40:43], v[152:155], v[190:193], v[40:43]
	v_mfma_f32_16x16x32_bf16 v[28:31], v[144:147], v[198:201], v[28:31]
	v_mfma_f32_16x16x32_bf16 v[24:27], v[152:155], v[198:201], v[24:27]
	v_mfma_f32_16x16x32_bf16 v[12:15], v[144:147], v[206:209], v[12:15]
	v_mfma_f32_16x16x32_bf16 v[8:11], v[152:155], v[206:209], v[8:11]
	v_mfma_f32_16x16x32_bf16 v[60:63], v[148:151], v[186:189], v[60:63]
	v_mfma_f32_16x16x32_bf16 v[56:59], v[156:159], v[186:189], v[56:59]
	v_mfma_f32_16x16x32_bf16 v[44:47], v[148:151], v[194:197], v[44:47]
	v_mfma_f32_16x16x32_bf16 v[40:43], v[156:159], v[194:197], v[40:43]
	v_mfma_f32_16x16x32_bf16 v[28:31], v[148:151], v[202:205], v[28:31]
	v_mfma_f32_16x16x32_bf16 v[24:27], v[156:159], v[202:205], v[24:27]
	v_mfma_f32_16x16x32_bf16 v[12:15], v[148:151], v[210:213], v[12:15]
	v_mfma_f32_16x16x32_bf16 v[8:11], v[156:159], v[210:213], v[8:11]
	v_mfma_f32_16x16x32_bf16 v[52:55], v[160:163], v[182:185], v[52:55]
	v_mfma_f32_16x16x32_bf16 v[48:51], v[174:177], v[182:185], v[48:51]
	v_mfma_f32_16x16x32_bf16 v[36:39], v[160:163], v[190:193], v[36:39]
	v_mfma_f32_16x16x32_bf16 v[32:35], v[174:177], v[190:193], v[32:35]
	v_mfma_f32_16x16x32_bf16 v[20:23], v[160:163], v[198:201], v[20:23]
	v_mfma_f32_16x16x32_bf16 v[16:19], v[174:177], v[198:201], v[16:19]
	v_mfma_f32_16x16x32_bf16 v[4:7], v[160:163], v[206:209], v[4:7]
	v_mfma_f32_16x16x32_bf16 v[0:3], v[174:177], v[206:209], v[0:3]
	v_mfma_f32_16x16x32_bf16 v[52:55], v[170:173], v[186:189], v[52:55]
	v_mfma_f32_16x16x32_bf16 v[48:51], v[178:181], v[186:189], v[48:51]
	v_mfma_f32_16x16x32_bf16 v[36:39], v[170:173], v[194:197], v[36:39]
	v_mfma_f32_16x16x32_bf16 v[32:35], v[178:181], v[194:197], v[32:35]
	v_mfma_f32_16x16x32_bf16 v[20:23], v[170:173], v[202:205], v[20:23]
	v_mfma_f32_16x16x32_bf16 v[16:19], v[178:181], v[202:205], v[16:19]
	v_mfma_f32_16x16x32_bf16 v[4:7], v[170:173], v[210:213], v[4:7]
	v_mfma_f32_16x16x32_bf16 v[0:3], v[178:181], v[210:213], v[0:3]
	s_setprio 0
	s_barrier
	s_add_i32 s51, 0, 0x18000
	s_add_i32 s52, 0, 0x1c000
	v_add_u32_e32 v156, s51, v165
	v_add_u32_e32 v178, s52, v165
	ds_read_b128 v[144:147], v156
	ds_read_b128 v[148:151], v156 offset:1024
	ds_read_b128 v[152:155], v156 offset:2048
	ds_read_b128 v[156:159], v156 offset:3072
	ds_read_b128 v[160:163], v178
	ds_read_b128 v[170:173], v178 offset:1024
	ds_read_b128 v[174:177], v178 offset:2048
	ds_read_b128 v[178:181], v178 offset:3072
	s_add_u32 s18, s18, 0xb0000
	s_addc_u32 s19, s19, 0
	s_mov_b32 m0, s26
	v_lshl_add_u64 v[222:223], s[18:19], 0, v[128:129]
	ds_read_b128 v[182:185], v169 offset:32768
	ds_read_b128 v[186:189], v169 offset:33792
	ds_read_b128 v[190:193], v169 offset:34816
	ds_read_b128 v[194:197], v169 offset:35840
	ds_read_b128 v[198:201], v169 offset:36864
	ds_read_b128 v[202:205], v169 offset:37888
	ds_read_b128 v[206:209], v169 offset:38912
	ds_read_b128 v[210:213], v169 offset:39936
	global_load_lds_dwordx4 v[222:223], off
	v_lshl_add_u64 v[222:223], s[18:19], 0, v[132:133]
	s_mov_b32 m0, s27
	s_nop 0
	global_load_lds_dwordx4 v[222:223], off
	s_waitcnt vmcnt(8)
	s_waitcnt lgkmcnt(0)
	s_barrier
	s_setprio 1
	s_waitcnt lgkmcnt(0)
	v_mfma_f32_16x16x32_bf16 v[124:127], v[144:147], v[182:185], v[124:127]
	v_mfma_f32_16x16x32_bf16 v[120:123], v[152:155], v[182:185], v[120:123]
	v_mfma_f32_16x16x32_bf16 v[108:111], v[144:147], v[190:193], v[108:111]
	v_mfma_f32_16x16x32_bf16 v[104:107], v[152:155], v[190:193], v[104:107]
	v_mfma_f32_16x16x32_bf16 v[92:95], v[144:147], v[198:201], v[92:95]
	v_mfma_f32_16x16x32_bf16 v[88:91], v[152:155], v[198:201], v[88:91]
	v_mfma_f32_16x16x32_bf16 v[76:79], v[144:147], v[206:209], v[76:79]
	v_mfma_f32_16x16x32_bf16 v[72:75], v[152:155], v[206:209], v[72:75]
	v_mfma_f32_16x16x32_bf16 v[124:127], v[148:151], v[186:189], v[124:127]
	v_mfma_f32_16x16x32_bf16 v[120:123], v[156:159], v[186:189], v[120:123]
	v_mfma_f32_16x16x32_bf16 v[108:111], v[148:151], v[194:197], v[108:111]
	v_mfma_f32_16x16x32_bf16 v[104:107], v[156:159], v[194:197], v[104:107]
	v_mfma_f32_16x16x32_bf16 v[92:95], v[148:151], v[202:205], v[92:95]
	v_mfma_f32_16x16x32_bf16 v[88:91], v[156:159], v[202:205], v[88:91]
	v_mfma_f32_16x16x32_bf16 v[76:79], v[148:151], v[210:213], v[76:79]
	v_mfma_f32_16x16x32_bf16 v[72:75], v[156:159], v[210:213], v[72:75]
	v_mfma_f32_16x16x32_bf16 v[116:119], v[160:163], v[182:185], v[116:119]
	v_mfma_f32_16x16x32_bf16 v[112:115], v[174:177], v[182:185], v[112:115]
	v_mfma_f32_16x16x32_bf16 v[100:103], v[160:163], v[190:193], v[100:103]
	v_mfma_f32_16x16x32_bf16 v[96:99], v[174:177], v[190:193], v[96:99]
	v_mfma_f32_16x16x32_bf16 v[84:87], v[160:163], v[198:201], v[84:87]
	v_mfma_f32_16x16x32_bf16 v[80:83], v[174:177], v[198:201], v[80:83]
	v_mfma_f32_16x16x32_bf16 v[68:71], v[160:163], v[206:209], v[68:71]
	v_mfma_f32_16x16x32_bf16 v[64:67], v[174:177], v[206:209], v[64:67]
	v_mfma_f32_16x16x32_bf16 v[116:119], v[170:173], v[186:189], v[116:119]
	v_mfma_f32_16x16x32_bf16 v[112:115], v[178:181], v[186:189], v[112:115]
	v_mfma_f32_16x16x32_bf16 v[100:103], v[170:173], v[194:197], v[100:103]
	v_mfma_f32_16x16x32_bf16 v[96:99], v[178:181], v[194:197], v[96:99]
	v_mfma_f32_16x16x32_bf16 v[84:87], v[170:173], v[202:205], v[84:87]
	v_mfma_f32_16x16x32_bf16 v[80:83], v[178:181], v[202:205], v[80:83]
	v_mfma_f32_16x16x32_bf16 v[68:71], v[170:173], v[210:213], v[68:71]
	v_mfma_f32_16x16x32_bf16 v[64:67], v[178:181], v[210:213], v[64:67]
	s_setprio 0
	s_barrier
	s_add_i32 s18, s51, s23
	v_lshl_add_u64 v[214:215], v[214:215], 0, s[6:7]
	s_mov_b32 m0, s18
	ds_read_b128 v[182:185], v169 offset:49152
	ds_read_b128 v[186:189], v169 offset:50176
	ds_read_b128 v[190:193], v169 offset:51200
	ds_read_b128 v[194:197], v169 offset:52224
	ds_read_b128 v[198:201], v169 offset:53248
	ds_read_b128 v[202:205], v169 offset:54272
	ds_read_b128 v[206:209], v169 offset:55296
	ds_read_b128 v[210:213], v169 offset:56320
	global_load_lds_dwordx4 v[214:215], off
	s_add_i32 m0, s18, 0x2000
	s_add_u32 s16, s16, 0xb0080
	v_lshl_add_u64 v[214:215], v[216:217], 0, s[6:7]
	s_addc_u32 s17, s17, 0
	s_add_i32 s18, s52, s23
	global_load_lds_dwordx4 v[214:215], off
	v_lshl_add_u64 v[214:215], s[16:17], 0, v[130:131]
	s_mov_b32 m0, s18
	s_nop 0
	global_load_lds_dwordx4 v[214:215], off
	v_lshl_add_u64 v[214:215], s[16:17], 0, v[134:135]
	s_add_i32 m0, s18, 0x2000
	s_nop 0
	global_load_lds_dwordx4 v[214:215], off
	v_lshl_add_u64 v[214:215], v[218:219], 0, s[6:7]
	s_mov_b32 m0, s35
	s_nop 0
	global_load_lds_dwordx4 v[214:215], off
	v_lshl_add_u64 v[214:215], v[220:221], 0, s[6:7]
	s_mov_b32 m0, s39
	s_nop 0
	global_load_lds_dwordx4 v[214:215], off
	s_waitcnt vmcnt(8)
	s_waitcnt lgkmcnt(0)
	s_barrier
	s_setprio 1
	s_waitcnt lgkmcnt(0)
	v_mfma_f32_16x16x32_bf16 v[60:63], v[144:147], v[182:185], v[60:63]
	v_mfma_f32_16x16x32_bf16 v[56:59], v[152:155], v[182:185], v[56:59]
	v_mfma_f32_16x16x32_bf16 v[44:47], v[144:147], v[190:193], v[44:47]
	v_mfma_f32_16x16x32_bf16 v[40:43], v[152:155], v[190:193], v[40:43]
	v_mfma_f32_16x16x32_bf16 v[28:31], v[144:147], v[198:201], v[28:31]
	v_mfma_f32_16x16x32_bf16 v[24:27], v[152:155], v[198:201], v[24:27]
	v_mfma_f32_16x16x32_bf16 v[12:15], v[144:147], v[206:209], v[12:15]
	v_mfma_f32_16x16x32_bf16 v[8:11], v[152:155], v[206:209], v[8:11]
	v_mfma_f32_16x16x32_bf16 v[60:63], v[148:151], v[186:189], v[60:63]
	v_mfma_f32_16x16x32_bf16 v[56:59], v[156:159], v[186:189], v[56:59]
	v_mfma_f32_16x16x32_bf16 v[44:47], v[148:151], v[194:197], v[44:47]
	v_mfma_f32_16x16x32_bf16 v[40:43], v[156:159], v[194:197], v[40:43]
	v_mfma_f32_16x16x32_bf16 v[28:31], v[148:151], v[202:205], v[28:31]
	v_mfma_f32_16x16x32_bf16 v[24:27], v[156:159], v[202:205], v[24:27]
	v_mfma_f32_16x16x32_bf16 v[12:15], v[148:151], v[210:213], v[12:15]
	v_mfma_f32_16x16x32_bf16 v[8:11], v[156:159], v[210:213], v[8:11]
	v_mfma_f32_16x16x32_bf16 v[52:55], v[160:163], v[182:185], v[52:55]
	v_mfma_f32_16x16x32_bf16 v[48:51], v[174:177], v[182:185], v[48:51]
	v_mfma_f32_16x16x32_bf16 v[36:39], v[160:163], v[190:193], v[36:39]
	v_mfma_f32_16x16x32_bf16 v[32:35], v[174:177], v[190:193], v[32:35]
	v_mfma_f32_16x16x32_bf16 v[20:23], v[160:163], v[198:201], v[20:23]
	v_mfma_f32_16x16x32_bf16 v[16:19], v[174:177], v[198:201], v[16:19]
	v_mfma_f32_16x16x32_bf16 v[4:7], v[160:163], v[206:209], v[4:7]
	v_mfma_f32_16x16x32_bf16 v[0:3], v[174:177], v[206:209], v[0:3]
	v_mfma_f32_16x16x32_bf16 v[52:55], v[170:173], v[186:189], v[52:55]
	v_mfma_f32_16x16x32_bf16 v[48:51], v[178:181], v[186:189], v[48:51]
	v_mfma_f32_16x16x32_bf16 v[36:39], v[170:173], v[194:197], v[36:39]
	v_mfma_f32_16x16x32_bf16 v[32:35], v[178:181], v[194:197], v[32:35]
	v_mfma_f32_16x16x32_bf16 v[20:23], v[170:173], v[202:205], v[20:23]
	v_mfma_f32_16x16x32_bf16 v[16:19], v[178:181], v[202:205], v[16:19]
	v_mfma_f32_16x16x32_bf16 v[4:7], v[170:173], v[210:213], v[4:7]
	v_mfma_f32_16x16x32_bf16 v[0:3], v[178:181], v[210:213], v[0:3]
	s_setprio 0
	s_barrier
	s_add_i32 s50, s50, 2
	s_add_u32 s14, s14, 0x100
	s_addc_u32 s15, s15, 0
	s_add_u32 s48, s48, 0x100
	s_addc_u32 s49, s49, 0
	s_cmp_gt_u32 s50, 41
	s_cbranch_scc0 .LBB0_1786
	s_and_b64 vcc, exec, s[8:9]
	s_cbranch_vccz .LBB0_1789
	s_barrier
